# prep KK/QK stage: column operand read once for 4 tiles, row operand reads batched with counted lgkmcnt, gcs/bts rows prefetched as b128
# baseline (speedup 1.0000x reference)
; __device__ __forceinline__ float shx(float v, int m, int lane) { return __int_as_float(__builtin_amdgcn_ds_bpermute((lane ^ m) << 2, __float_as_int(v))); }
; __device__ __forceinline__ float silu_f(float x) { return x * __builtin_amdgcn_rcpf(1.0f + fexp(-x)); }
; __device__ __forceinline__ void phase_dnprep(h16* Pdn, const h16* halo, const float* bd, const float* convw, const float* a_log, const float* dt_bias,
;                              h16* Tg, h16* qkg, float* gcg, float* betag, float* s2g, LAS unsigned char* ldsl, unsigned char* ldsb) {
;     ...
;         {
;             const int rr = lane >> 3, cp = lane & 7, i = 8 * w + rr;
;             h16* gp = Pdn + (tok0 + i) * 4096 + h * 128 + 16 * cp;
;             const float bt_i = bts[i];
; #pragma unroll
;             for (int seg = 0; seg < 3; ++seg) {
;                 float y[16];
; #pragma unroll
;                 for (int e = 0; e < 16; ++e) y[e] = 0.f;
; #pragma unroll
;                 for (int j = 0; j < 4; ++j) {
;                     const h16x8 x0 = *(const h16x8*)(raw + (i + j) * RP + seg * 128 + 16 * cp), x1 = *(const h16x8*)(raw + (i + j) * RP + seg * 128 + 16 * cp + 8);
;                     const f32x4* cwp = (const f32x4*)(cw + j * 384 + seg * 128 + 16 * cp);
;                     const f32x4 c0 = cwp[0], c1 = cwp[1], c2 = cwp[2], c3 = cwp[3];
; #pragma unroll
;                     for (int e = 0; e < 4; ++e) {
;                         y[e] += c0[e] * (float)x0[e]; y[4 + e] += c1[e] * (float)x0[4 + e];
;                         y[8 + e] += c2[e] * (float)x1[e]; y[12 + e] += c3[e] * (float)x1[4 + e];
;                     }
;                 }
; #pragma unroll
;                 for (int e = 0; e < 16; ++e) y[e] = silu_f(y[e]);
;                 float scl = bt_i;
;                 if (seg < 2) {
;                     float ss = 0.f;
; #pragma unroll
;                     for (int e = 0; e < 16; ++e) ss += y[e] * y[e];
;                     ss += shx(ss, 1, lane); ss += shx(ss, 2, lane); ss += shx(ss, 4, lane);
;                     scl = rsqrtf(ss + 1e-6f) * (seg == 0 ? 0.08838834764831845f : 1.0f);
;                 }
.LBB0_354:
	s_nop 0
	s_nop 0
	v_readlane_b32 s69, v254, 52
	v_lshrrev_b32_e32 v0, 3, v99
	s_mov_b32 s45, s69
	v_or_b32_e32 v2, s37, v0
	s_nop 7
	s_nop 0
	v_readlane_b32 s71, v254, 54
	v_readlane_b32 s72, v254, 55
	v_readlane_b32 s73, v254, 56
	s_nop 1
	v_writelane_b32 v254, s36, 43
	s_lshl_b32 s0, s20, 12
	s_or_b32 s0, s0, s21
	v_writelane_b32 v254, s37, 44
	v_writelane_b32 v254, s38, 45
	v_writelane_b32 v254, s39, 46
	v_writelane_b32 v254, s40, 47
	v_writelane_b32 v254, s41, 48
	v_writelane_b32 v254, s42, 49
	v_writelane_b32 v254, s43, 50
	v_writelane_b32 v254, s44, 51
	v_writelane_b32 v254, s45, 52
	v_add_lshl_u32 v32, s0, v2, 12
	v_writelane_b32 v254, s46, 53
	v_lshlrev_b32_e32 v3, 4, v82
	v_lshl_add_u64 v[0:1], v[32:33], 1, s[86:87]
	s_mov_b32 s21, s69
	s_lshl_b32 s20, s3, 8
	v_writelane_b32 v254, s47, 54
	v_and_b32_e32 v3, 0x70, v3
	v_writelane_b32 v254, s48, 55
	v_lshl_add_u64 v[0:1], v[0:1], 0, s[20:21]
	v_lshlrev_b32_e32 v32, 1, v3
	v_writelane_b32 v254, s49, 56
	v_lshl_add_u64 v[86:87], v[0:1], 0, v[32:33]
	v_lshl_add_u32 v0, v2, 2, 0
	v_writelane_b32 v254, s50, 57
	v_add_u32_e32 v0, 0x27700, v0
	v_writelane_b32 v254, s51, 58
	ds_read_b32 v88, v0
	v_lshl_add_u32 v0, v3, 2, 0
	s_movk_i32 s0, 0x110
	v_add_u32_e32 v83, 0x25e00, v0
	v_mul_lo_u32 v0, v2, s0
	v_readlane_b32 s1, v254, 39
	v_readlane_b32 s0, v254, 38
	v_xor_b32_e32 v104, 4, v4
	v_add3_u32 v105, s1, v32, v0
	s_movk_i32 s1, 0x300
	v_add3_u32 v101, s0, v32, v0
	v_mul_lo_u32 v0, v2, s1
	v_add3_u32 v32, s78, v32, v0
	v_xor_b32_e32 v103, 8, v4
	v_xor_b32_e32 v102, 16, v4
	ds_read_b128 v[0:3], v32
	ds_read_b128 v[50:53], v32 offset:16
	ds_read_b128 v[38:41], v83
	ds_read_b128 v[8:11], v83 offset:16
	ds_read_b128 v[106:109], v83 offset:32
	ds_read_b128 v[58:61], v83 offset:48
	ds_read_b128 v[4:7], v32 offset:768
	ds_read_b128 v[54:57], v32 offset:784
	ds_read_b128 v[42:45], v83 offset:1536
	ds_read_b128 v[20:23], v83 offset:1552
	ds_read_b128 v[110:113], v83 offset:1568
	ds_read_b128 v[70:73], v83 offset:1584
	ds_read_b128 v[16:19], v32 offset:1536
	ds_read_b128 v[66:69], v32 offset:1552
	ds_read_b128 v[46:49], v83 offset:3072
	ds_read_b128 v[28:31], v83 offset:3088
	ds_read_b128 v[114:117], v83 offset:3104
	ds_read_b128 v[78:81], v83 offset:3120
	ds_read_b128 v[24:27], v32 offset:2304
	ds_read_b128 v[74:77], v32 offset:2320
	ds_read_b128 v[34:37], v83 offset:4608
	ds_read_b128 v[12:15], v83 offset:4624
	ds_read_b128 v[118:121], v83 offset:4640
	ds_read_b128 v[62:65], v83 offset:4656
	s_waitcnt lgkmcnt(0)
	v_cvt_f32_f16_e32 v90, v50
	v_cvt_f32_f16_sdwa v91, v50 dst_sel:DWORD dst_unused:UNUSED_PAD src0_sel:WORD_1
	v_cvt_f32_f16_e32 v92, v54
	v_cvt_f32_f16_sdwa v93, v54 dst_sel:DWORD dst_unused:UNUSED_PAD src0_sel:WORD_1
	v_cvt_f32_f16_e32 v54, v55
	v_pk_fma_f32 v[90:91], v[106:107], v[90:91], 0 op_sel_hi:[1,1,0]
	v_cvt_f32_f16_sdwa v55, v55 dst_sel:DWORD dst_unused:UNUSED_PAD src0_sel:WORD_1
	v_pk_fma_f32 v[90:91], v[110:111], v[92:93], v[90:91]
	v_cvt_f32_f16_e32 v92, v66
	v_cvt_f32_f16_sdwa v93, v66 dst_sel:DWORD dst_unused:UNUSED_PAD src0_sel:WORD_1
	v_cvt_f32_f16_e32 v66, v52
	s_mov_b32 s1, 0x800000
	v_and_b32_e32 v100, 15, v82
	v_pk_fma_f32 v[90:91], v[114:115], v[92:93], v[90:91]
	v_cvt_f32_f16_e32 v92, v74
	v_cvt_f32_f16_sdwa v93, v74 dst_sel:DWORD dst_unused:UNUSED_PAD src0_sel:WORD_1
	v_lshrrev_b32_e32 v84, 4, v99
	v_pk_fma_f32 v[90:91], v[118:119], v[92:93], v[90:91]
	s_nop 0
	v_mul_f32_e32 v50, 0xbfb8aa3b, v90
	v_exp_f32_e32 v50, v50
	s_nop 0
	v_add_f32_e32 v50, 1.0, v50
	v_rcp_f32_e32 v92, v50
	v_mul_f32_e32 v50, 0xbfb8aa3b, v91
	v_exp_f32_e32 v50, v50
	s_nop 0
	v_add_f32_e32 v50, 1.0, v50
	v_rcp_f32_e32 v93, v50
	v_cvt_f32_f16_e32 v50, v51
	v_cvt_f32_f16_sdwa v51, v51 dst_sel:DWORD dst_unused:UNUSED_PAD src0_sel:WORD_1
	v_pk_mul_f32 v[90:91], v[90:91], v[92:93]
	s_nop 0
	v_pk_mul_f32 v[92:93], v[90:91], v[90:91]
	v_pk_fma_f32 v[50:51], v[108:109], v[50:51], 0 op_sel_hi:[1,1,0]
	s_nop 0
	v_pk_fma_f32 v[50:51], v[112:113], v[54:55], v[50:51]
	v_cvt_f32_f16_e32 v54, v67
	v_cvt_f32_f16_sdwa v55, v67 dst_sel:DWORD dst_unused:UNUSED_PAD src0_sel:WORD_1
	v_cvt_f32_f16_sdwa v67, v52 dst_sel:DWORD dst_unused:UNUSED_PAD src0_sel:WORD_1
	v_pk_fma_f32 v[50:51], v[116:117], v[54:55], v[50:51]
	v_pk_fma_f32 v[58:59], v[58:59], v[66:67], 0 op_sel_hi:[1,1,0]
	v_cvt_f32_f16_e32 v66, v56
	v_cvt_f32_f16_sdwa v67, v56 dst_sel:DWORD dst_unused:UNUSED_PAD src0_sel:WORD_1
	v_cvt_f32_f16_e32 v56, v57
	v_cvt_f32_f16_sdwa v57, v57 dst_sel:DWORD dst_unused:UNUSED_PAD src0_sel:WORD_1
	v_cvt_f32_f16_e32 v54, v75
	v_pk_fma_f32 v[58:59], v[70:71], v[66:67], v[58:59]
	v_cvt_f32_f16_e32 v66, v68
	v_cvt_f32_f16_sdwa v67, v68 dst_sel:DWORD dst_unused:UNUSED_PAD src0_sel:WORD_1
	v_cvt_f32_f16_sdwa v55, v75 dst_sel:DWORD dst_unused:UNUSED_PAD src0_sel:WORD_1
	v_pk_fma_f32 v[58:59], v[78:79], v[66:67], v[58:59]
	v_cvt_f32_f16_e32 v66, v76
	v_cvt_f32_f16_sdwa v67, v76 dst_sel:DWORD dst_unused:UNUSED_PAD src0_sel:WORD_1
	v_pk_fma_f32 v[50:51], v[120:121], v[54:55], v[50:51]
	v_pk_fma_f32 v[58:59], v[62:63], v[66:67], v[58:59]
	s_nop 0
	v_mul_f32_e32 v52, 0xbfb8aa3b, v58
	v_exp_f32_e32 v52, v52
	v_mul_f32_e32 v54, 0xbfb8aa3b, v50
	v_mul_f32_e32 v55, 0xbfb8aa3b, v51
	v_exp_f32_e32 v54, v54
	v_add_f32_e32 v52, 1.0, v52
	v_rcp_f32_e32 v62, v52
	v_mul_f32_e32 v52, 0xbfb8aa3b, v59
	v_exp_f32_e32 v52, v52
	v_exp_f32_e32 v55, v55
	v_add_f32_e32 v54, 1.0, v54
	v_rcp_f32_e32 v54, v54
	v_add_f32_e32 v52, 1.0, v52
	v_rcp_f32_e32 v63, v52
	v_cvt_f32_f16_e32 v52, v53
	v_cvt_f32_f16_sdwa v53, v53 dst_sel:DWORD dst_unused:UNUSED_PAD src0_sel:WORD_1
	v_add_f32_e32 v55, 1.0, v55
	v_rcp_f32_e32 v55, v55
; __device__ __forceinline__ float shx(float v, int m, int lane) { return __int_as_float(__builtin_amdgcn_ds_bpermute((lane ^ m) << 2, __float_as_int(v))); }
; __device__ __forceinline__ float silu_f(float x) { return x * __builtin_amdgcn_rcpf(1.0f + fexp(-x)); }
; __device__ __forceinline__ void phase_dnprep(h16* Pdn, const h16* halo, const float* bd, const float* convw, const float* a_log, const float* dt_bias,
;                              h16* Tg, h16* qkg, float* gcg, float* betag, float* s2g, LAS unsigned char* ldsl, unsigned char* ldsb) {
;     ...
;                 for (int j = 0; j < 4; ++j) {
;                     const h16x8 x0 = *(const h16x8*)(raw + (i + j) * RP + seg * 128 + 16 * cp), x1 = *(const h16x8*)(raw + (i + j) * RP + seg * 128 + 16 * cp + 8);
;                     const f32x4* cwp = (const f32x4*)(cw + j * 384 + seg * 128 + 16 * cp);
;                     const f32x4 c0 = cwp[0], c1 = cwp[1], c2 = cwp[2], c3 = cwp[3];
; #pragma unroll
;                     for (int e = 0; e < 4; ++e) {
;                         y[e] += c0[e] * (float)x0[e]; y[4 + e] += c1[e] * (float)x0[4 + e];
;                         y[8 + e] += c2[e] * (float)x1[e]; y[12 + e] += c3[e] * (float)x1[4 + e];
;                     }
;                 }
; #pragma unroll
;                 for (int e = 0; e < 16; ++e) y[e] = silu_f(y[e]);
;                 float scl = bt_i;
;                 if (seg < 2) {
;                     float ss = 0.f;
; #pragma unroll
;                     for (int e = 0; e < 16; ++e) ss += y[e] * y[e];
;                     ss += shx(ss, 1, lane); ss += shx(ss, 2, lane); ss += shx(ss, 4, lane);
;                     scl = rsqrtf(ss + 1e-6f) * (seg == 0 ? 0.08838834764831845f : 1.0f);
	v_pk_mul_f32 v[58:59], v[58:59], v[62:63]
	v_pk_fma_f32 v[52:53], v[60:61], v[52:53], 0 op_sel_hi:[1,1,0]
	v_cvt_f32_f16_e32 v60, v0
	v_cvt_f32_f16_sdwa v61, v0 dst_sel:DWORD dst_unused:UNUSED_PAD src0_sel:WORD_1
	v_pk_fma_f32 v[52:53], v[72:73], v[56:57], v[52:53]
	v_cvt_f32_f16_e32 v56, v69
	v_cvt_f32_f16_sdwa v57, v69 dst_sel:DWORD dst_unused:UNUSED_PAD src0_sel:WORD_1
	v_pk_fma_f32 v[38:39], v[38:39], v[60:61], 0 op_sel_hi:[1,1,0]
	v_cvt_f32_f16_e32 v60, v4
	v_cvt_f32_f16_sdwa v61, v4 dst_sel:DWORD dst_unused:UNUSED_PAD src0_sel:WORD_1
	v_cvt_f32_f16_e32 v4, v5
	v_cvt_f32_f16_sdwa v5, v5 dst_sel:DWORD dst_unused:UNUSED_PAD src0_sel:WORD_1
	v_pk_fma_f32 v[52:53], v[80:81], v[56:57], v[52:53]
	v_pk_fma_f32 v[38:39], v[42:43], v[60:61], v[38:39]
	v_cvt_f32_f16_e32 v42, v16
	v_cvt_f32_f16_sdwa v43, v16 dst_sel:DWORD dst_unused:UNUSED_PAD src0_sel:WORD_1
	v_cvt_f32_f16_e32 v16, v2
	v_cvt_f32_f16_e32 v56, v77
	v_cvt_f32_f16_sdwa v57, v77 dst_sel:DWORD dst_unused:UNUSED_PAD src0_sel:WORD_1
	v_pk_fma_f32 v[38:39], v[46:47], v[42:43], v[38:39]
	v_cvt_f32_f16_e32 v42, v24
	v_cvt_f32_f16_sdwa v43, v24 dst_sel:DWORD dst_unused:UNUSED_PAD src0_sel:WORD_1
	v_pk_fma_f32 v[52:53], v[64:65], v[56:57], v[52:53]
	v_pk_mul_f32 v[50:51], v[50:51], v[54:55]
	v_mul_f32_e32 v56, 0xbfb8aa3b, v52
	v_pk_fma_f32 v[34:35], v[34:35], v[42:43], v[38:39]
	v_mul_f32_e32 v57, 0xbfb8aa3b, v53
	v_mul_f32_e32 v0, 0xbfb8aa3b, v34
	v_exp_f32_e32 v0, v0
	v_exp_f32_e32 v56, v56
	v_exp_f32_e32 v57, v57
	v_pk_mul_f32 v[54:55], v[50:51], v[50:51]
	v_add_f32_e32 v0, 1.0, v0
	v_rcp_f32_e32 v38, v0
	v_mul_f32_e32 v0, 0xbfb8aa3b, v35
	v_exp_f32_e32 v0, v0
	v_add_f32_e32 v56, 1.0, v56
	v_add_f32_e32 v57, 1.0, v57
	v_rcp_f32_e32 v56, v56
	v_add_f32_e32 v0, 1.0, v0
	v_rcp_f32_e32 v39, v0
	v_cvt_f32_f16_e32 v0, v1
	v_cvt_f32_f16_sdwa v1, v1 dst_sel:DWORD dst_unused:UNUSED_PAD src0_sel:WORD_1
	v_rcp_f32_e32 v57, v57
	v_pk_mul_f32 v[34:35], v[34:35], v[38:39]
	v_pk_mul_f32 v[62:63], v[58:59], v[58:59]
	v_pk_fma_f32 v[0:1], v[40:41], v[0:1], 0 op_sel_hi:[1,1,0]
	v_pk_mul_f32 v[38:39], v[34:35], v[34:35]
	v_pk_fma_f32 v[0:1], v[44:45], v[4:5], v[0:1]
	v_cvt_f32_f16_e32 v4, v17
	v_cvt_f32_f16_sdwa v5, v17 dst_sel:DWORD dst_unused:UNUSED_PAD src0_sel:WORD_1
	v_cvt_f32_f16_sdwa v17, v2 dst_sel:DWORD dst_unused:UNUSED_PAD src0_sel:WORD_1
	v_pk_mul_f32 v[52:53], v[52:53], v[56:57]
	v_pk_fma_f32 v[0:1], v[48:49], v[4:5], v[0:1]
	v_pk_fma_f32 v[8:9], v[8:9], v[16:17], 0 op_sel_hi:[1,1,0]
	v_cvt_f32_f16_e32 v16, v6
	v_cvt_f32_f16_sdwa v17, v6 dst_sel:DWORD dst_unused:UNUSED_PAD src0_sel:WORD_1
	v_cvt_f32_f16_e32 v6, v7
	v_cvt_f32_f16_sdwa v7, v7 dst_sel:DWORD dst_unused:UNUSED_PAD src0_sel:WORD_1
	v_cvt_f32_f16_e32 v4, v25
	v_pk_fma_f32 v[8:9], v[20:21], v[16:17], v[8:9]
	v_cvt_f32_f16_e32 v16, v18
	v_cvt_f32_f16_sdwa v17, v18 dst_sel:DWORD dst_unused:UNUSED_PAD src0_sel:WORD_1
	v_cvt_f32_f16_sdwa v5, v25 dst_sel:DWORD dst_unused:UNUSED_PAD src0_sel:WORD_1
	v_pk_mul_f32 v[56:57], v[52:53], v[52:53]
	v_pk_fma_f32 v[8:9], v[28:29], v[16:17], v[8:9]
	v_cvt_f32_f16_e32 v16, v26
	v_cvt_f32_f16_sdwa v17, v26 dst_sel:DWORD dst_unused:UNUSED_PAD src0_sel:WORD_1
	v_pk_fma_f32 v[0:1], v[36:37], v[4:5], v[0:1]
	v_pk_fma_f32 v[8:9], v[12:13], v[16:17], v[8:9]
	s_nop 0
	v_mul_f32_e32 v2, 0xbfb8aa3b, v8
	v_exp_f32_e32 v2, v2
	v_mul_f32_e32 v4, 0xbfb8aa3b, v0
	v_mul_f32_e32 v5, 0xbfb8aa3b, v1
	v_exp_f32_e32 v4, v4
	v_add_f32_e32 v2, 1.0, v2
	v_rcp_f32_e32 v12, v2
	v_mul_f32_e32 v2, 0xbfb8aa3b, v9
	v_exp_f32_e32 v2, v2
	v_exp_f32_e32 v5, v5
	v_add_f32_e32 v4, 1.0, v4
	v_rcp_f32_e32 v4, v4
	v_add_f32_e32 v2, 1.0, v2
	v_rcp_f32_e32 v13, v2
	v_cvt_f32_f16_e32 v2, v3
	v_cvt_f32_f16_sdwa v3, v3 dst_sel:DWORD dst_unused:UNUSED_PAD src0_sel:WORD_1
	v_add_f32_e32 v5, 1.0, v5
	v_rcp_f32_e32 v5, v5
	v_pk_mul_f32 v[8:9], v[8:9], v[12:13]
	v_pk_fma_f32 v[2:3], v[10:11], v[2:3], 0 op_sel_hi:[1,1,0]
	v_pk_mul_f32 v[12:13], v[8:9], v[8:9]
	v_pk_fma_f32 v[2:3], v[22:23], v[6:7], v[2:3]
	v_cvt_f32_f16_e32 v6, v19
	v_cvt_f32_f16_sdwa v7, v19 dst_sel:DWORD dst_unused:UNUSED_PAD src0_sel:WORD_1
	v_pk_mul_f32 v[0:1], v[0:1], v[4:5]
	v_pk_fma_f32 v[2:3], v[30:31], v[6:7], v[2:3]
	v_cvt_f32_f16_e32 v6, v27
	v_cvt_f32_f16_sdwa v7, v27 dst_sel:DWORD dst_unused:UNUSED_PAD src0_sel:WORD_1
	v_pk_mul_f32 v[4:5], v[0:1], v[0:1]
	v_pk_fma_f32 v[2:3], v[14:15], v[6:7], v[2:3]
	s_nop 0
	v_mul_f32_e32 v6, 0xbfb8aa3b, v2
	v_mul_f32_e32 v7, 0xbfb8aa3b, v3
	v_exp_f32_e32 v6, v6
	v_exp_f32_e32 v7, v7
	v_add_f32_e32 v6, 1.0, v6
	v_add_f32_e32 v7, 1.0, v7
	v_rcp_f32_e32 v6, v6
	v_rcp_f32_e32 v7, v7
	s_nop 0
	v_pk_mul_f32 v[10:11], v[2:3], v[6:7]
	v_add_f32_e32 v6, v38, v39
	v_add_f32_e32 v4, v4, v6
	v_add_f32_e32 v4, v5, v4
	v_add_f32_e32 v4, v12, v4
	v_pk_mul_f32 v[2:3], v[10:11], v[10:11]
	v_add_f32_e32 v4, v13, v4
	v_add_f32_e32 v2, v2, v4
	v_add_f32_e32 v2, v3, v2
	v_add_f32_e32 v2, v92, v2
	v_add_f32_e32 v2, v93, v2
	v_add_f32_e32 v2, v54, v2
	v_add_f32_e32 v2, v55, v2
	v_add_f32_e32 v2, v62, v2
	v_add_f32_e32 v2, v63, v2
	v_add_f32_e32 v2, v56, v2
	v_add_f32_e32 v2, v57, v2
	ds_bpermute_b32 v3, v104, v2
	s_waitcnt lgkmcnt(0)
	v_add_f32_e32 v2, v2, v3
	ds_bpermute_b32 v3, v103, v2
	s_waitcnt lgkmcnt(0)
	v_add_f32_e32 v2, v2, v3
	ds_bpermute_b32 v3, v102, v2
	s_waitcnt lgkmcnt(0)
; __device__ __forceinline__ float shx(float v, int m, int lane) { return __int_as_float(__builtin_amdgcn_ds_bpermute((lane ^ m) << 2, __float_as_int(v))); }
; __device__ __forceinline__ void phase_dnprep(h16* Pdn, const h16* halo, const float* bd, const float* convw, const float* a_log, const float* dt_bias,
;                              h16* Tg, h16* qkg, float* gcg, float* betag, float* s2g, LAS unsigned char* ldsl, unsigned char* ldsb) {
;     ...
;                 for (int j = 0; j < 4; ++j) {
;                     const h16x8 x0 = *(const h16x8*)(raw + (i + j) * RP + seg * 128 + 16 * cp), x1 = *(const h16x8*)(raw + (i + j) * RP + seg * 128 + 16 * cp + 8);
;                     const f32x4* cwp = (const f32x4*)(cw + j * 384 + seg * 128 + 16 * cp);
;                     const f32x4 c0 = cwp[0], c1 = cwp[1], c2 = cwp[2], c3 = cwp[3];
; #pragma unroll
;                     for (int e = 0; e < 4; ++e) {
;                         y[e] += c0[e] * (float)x0[e]; y[4 + e] += c1[e] * (float)x0[4 + e];
;                         y[8 + e] += c2[e] * (float)x1[e]; y[12 + e] += c3[e] * (float)x1[4 + e];
;                     }
;                 }
;     ...
;                     ss += shx(ss, 1, lane); ss += shx(ss, 2, lane); ss += shx(ss, 4, lane);
;                     scl = rsqrtf(ss + 1e-6f) * (seg == 0 ? 0.08838834764831845f : 1.0f);
;                 }
;                 h16x8 o0, o1;
; #pragma unroll
;                 for (int e = 0; e < 8; ++e) { o0[e] = (h16)(y[e] * scl); o1[e] = (h16)(y[8 + e] * scl); }
;                 if (seg == 0) { *(h16x8*)(qn + i * 136 + 16 * cp) = o0; *(h16x8*)(qn + i * 136 + 16 * cp + 8) = o1; }
;                 if (seg == 1) { *(h16x8*)(kn + i * 136 + 16 * cp) = o0; *(h16x8*)(kn + i * 136 + 16 * cp + 8) = o1; }
;                 gst((h16x8*)(gp + seg * 1024), o0); gst((h16x8*)(gp + seg * 1024 + 8), o1);
;             }
	v_add_f32_e32 v2, v2, v3
	v_add_f32_e32 v2, 0x358637bd, v2
	v_cmp_gt_f32_e32 vcc, s1, v2
	v_mul_f32_e32 v3, 0x4b800000, v2
	s_nop 0
	v_cndmask_b32_e32 v2, v2, v3, vcc
	v_rsq_f32_e32 v2, v2
	s_nop 0
	v_mul_f32_e32 v3, 0x45800000, v2
	v_cndmask_b32_e32 v2, v2, v3, vcc
	v_mul_f32_e32 v12, 0x3db504f3, v2
	v_pk_mul_f32 v[2:3], v[34:35], v[12:13] op_sel_hi:[1,0]
	v_pk_mul_f32 v[0:1], v[0:1], v[12:13] op_sel_hi:[1,0]
	v_cvt_pk_f16_f32 v2, v2, v3
	v_cvt_pk_f16_f32 v3, v0, v1
	v_pk_mul_f32 v[0:1], v[50:51], v[12:13] op_sel_hi:[1,0]
	v_pk_mul_f32 v[4:5], v[90:91], v[12:13] op_sel_hi:[1,0]
	v_cvt_pk_f16_f32 v7, v0, v1
	v_pk_mul_f32 v[0:1], v[8:9], v[12:13] op_sel_hi:[1,0]
	v_cvt_pk_f16_f32 v6, v4, v5
	v_cvt_pk_f16_f32 v4, v0, v1
	v_pk_mul_f32 v[0:1], v[58:59], v[12:13] op_sel_hi:[1,0]
	s_nop 0
	v_cvt_pk_f16_f32 v8, v0, v1
	v_pk_mul_f32 v[0:1], v[10:11], v[12:13] op_sel_hi:[1,0]
	s_nop 0
	v_cvt_pk_f16_f32 v5, v0, v1
	v_pk_mul_f32 v[0:1], v[52:53], v[12:13] op_sel_hi:[1,0]
	s_nop 0
	v_cvt_pk_f16_f32 v9, v0, v1
	ds_write_b128 v105, v[2:5]
	ds_write_b128 v105, v[6:9] offset:16
	global_store_dwordx4 v[86:87], v[2:5], off
	global_store_dwordx4 v[86:87], v[6:9], off offset:16
	ds_read_b128 v[24:27], v32 offset:256
	ds_read_b128 v[74:77], v32 offset:272
	ds_read_b128 v[46:49], v83 offset:512
	ds_read_b128 v[28:31], v83 offset:528
	ds_read_b128 v[106:109], v83 offset:544
	ds_read_b128 v[78:81], v83 offset:560
	ds_read_b128 v[16:19], v32 offset:1024
	ds_read_b128 v[62:65], v32 offset:1040
	ds_read_b128 v[42:45], v83 offset:2048
	ds_read_b128 v[20:23], v83 offset:2064
	ds_read_b128 v[110:113], v83 offset:2080
	ds_read_b128 v[66:69], v83 offset:2096
	ds_read_b128 v[4:7], v32 offset:1792
	ds_read_b128 v[54:57], v32 offset:1808
	ds_read_b128 v[38:41], v83 offset:3584
	ds_read_b128 v[12:15], v83 offset:3600
	ds_read_b128 v[114:117], v83 offset:3616
	ds_read_b128 v[70:73], v83 offset:3632
	ds_read_b128 v[8:11], v32 offset:2560
	ds_read_b128 v[58:61], v32 offset:2576
	ds_read_b128 v[34:37], v83 offset:5120
	ds_read_b128 v[0:3], v83 offset:5136
	ds_read_b128 v[118:121], v83 offset:5152
	ds_read_b128 v[50:53], v83 offset:5168
	s_waitcnt lgkmcnt(0)
	v_cvt_f32_f16_e32 v90, v74
	v_cvt_f32_f16_sdwa v91, v74 dst_sel:DWORD dst_unused:UNUSED_PAD src0_sel:WORD_1
	v_cvt_f32_f16_e32 v92, v62
	v_cvt_f32_f16_sdwa v93, v62 dst_sel:DWORD dst_unused:UNUSED_PAD src0_sel:WORD_1
	v_cvt_f32_f16_e32 v74, v75
	v_pk_fma_f32 v[90:91], v[106:107], v[90:91], 0 op_sel_hi:[1,1,0]
	v_cvt_f32_f16_sdwa v75, v75 dst_sel:DWORD dst_unused:UNUSED_PAD src0_sel:WORD_1
	v_pk_fma_f32 v[90:91], v[110:111], v[92:93], v[90:91]
	v_cvt_f32_f16_e32 v92, v54
	v_cvt_f32_f16_sdwa v93, v54 dst_sel:DWORD dst_unused:UNUSED_PAD src0_sel:WORD_1
	v_cvt_f32_f16_e32 v62, v63
	v_cvt_f32_f16_sdwa v63, v63 dst_sel:DWORD dst_unused:UNUSED_PAD src0_sel:WORD_1
	v_pk_fma_f32 v[74:75], v[108:109], v[74:75], 0 op_sel_hi:[1,1,0]
	v_pk_fma_f32 v[90:91], v[114:115], v[92:93], v[90:91]
	v_cvt_f32_f16_e32 v92, v58
	v_cvt_f32_f16_sdwa v93, v58 dst_sel:DWORD dst_unused:UNUSED_PAD src0_sel:WORD_1
	v_pk_fma_f32 v[62:63], v[112:113], v[62:63], v[74:75]
	v_cvt_f32_f16_e32 v74, v64
	v_cvt_f32_f16_sdwa v75, v64 dst_sel:DWORD dst_unused:UNUSED_PAD src0_sel:WORD_1
	v_pk_fma_f32 v[90:91], v[118:119], v[92:93], v[90:91]
	v_cvt_f32_f16_e32 v64, v65
	v_mul_f32_e32 v54, 0xbfb8aa3b, v90
	v_exp_f32_e32 v54, v54
	v_cvt_f32_f16_sdwa v65, v65 dst_sel:DWORD dst_unused:UNUSED_PAD src0_sel:WORD_1
	v_cvt_f32_f16_e32 v58, v59
	v_cvt_f32_f16_sdwa v59, v59 dst_sel:DWORD dst_unused:UNUSED_PAD src0_sel:WORD_1
	v_add_f32_e32 v54, 1.0, v54
	v_rcp_f32_e32 v92, v54
	v_mul_f32_e32 v54, 0xbfb8aa3b, v91
	v_exp_f32_e32 v54, v54
	s_nop 0
	v_add_f32_e32 v54, 1.0, v54
	v_rcp_f32_e32 v93, v54
	v_cvt_f32_f16_e32 v54, v55
	v_cvt_f32_f16_sdwa v55, v55 dst_sel:DWORD dst_unused:UNUSED_PAD src0_sel:WORD_1
	v_pk_mul_f32 v[90:91], v[90:91], v[92:93]
	s_nop 0
	v_pk_mul_f32 v[92:93], v[90:91], v[90:91]
	v_pk_fma_f32 v[54:55], v[116:117], v[54:55], v[62:63]
	v_cvt_f32_f16_e32 v62, v76
	v_cvt_f32_f16_sdwa v63, v76 dst_sel:DWORD dst_unused:UNUSED_PAD src0_sel:WORD_1
	v_pk_fma_f32 v[54:55], v[120:121], v[58:59], v[54:55]
	v_pk_fma_f32 v[62:63], v[78:79], v[62:63], 0 op_sel_hi:[1,1,0]
	s_nop 0
	v_pk_fma_f32 v[62:63], v[66:67], v[74:75], v[62:63]
	v_cvt_f32_f16_e32 v66, v56
	v_cvt_f32_f16_sdwa v67, v56 dst_sel:DWORD dst_unused:UNUSED_PAD src0_sel:WORD_1
	v_mul_f32_e32 v58, 0xbfb8aa3b, v54
	v_mul_f32_e32 v59, 0xbfb8aa3b, v55
	v_exp_f32_e32 v58, v58
	v_pk_fma_f32 v[62:63], v[70:71], v[66:67], v[62:63]
	v_cvt_f32_f16_e32 v66, v60
	v_cvt_f32_f16_sdwa v67, v60 dst_sel:DWORD dst_unused:UNUSED_PAD src0_sel:WORD_1
	v_cvt_f32_f16_e32 v60, v61
	v_cvt_f32_f16_sdwa v61, v61 dst_sel:DWORD dst_unused:UNUSED_PAD src0_sel:WORD_1
	v_exp_f32_e32 v59, v59
	v_pk_fma_f32 v[50:51], v[50:51], v[66:67], v[62:63]
	v_cvt_f32_f16_e32 v66, v77
	v_mul_f32_e32 v56, 0xbfb8aa3b, v50
	v_exp_f32_e32 v56, v56
	v_cvt_f32_f16_sdwa v67, v77 dst_sel:DWORD dst_unused:UNUSED_PAD src0_sel:WORD_1
	v_add_f32_e32 v58, 1.0, v58
	v_add_f32_e32 v59, 1.0, v59
	v_add_f32_e32 v56, 1.0, v56
	v_rcp_f32_e32 v62, v56
	v_mul_f32_e32 v56, 0xbfb8aa3b, v51
	v_exp_f32_e32 v56, v56
	v_pk_fma_f32 v[66:67], v[80:81], v[66:67], 0 op_sel_hi:[1,1,0]
	v_rcp_f32_e32 v58, v58
	v_pk_fma_f32 v[64:65], v[68:69], v[64:65], v[66:67]
	v_add_f32_e32 v56, 1.0, v56
	v_rcp_f32_e32 v63, v56
	v_cvt_f32_f16_e32 v56, v57
	v_cvt_f32_f16_sdwa v57, v57 dst_sel:DWORD dst_unused:UNUSED_PAD src0_sel:WORD_1
	v_rcp_f32_e32 v59, v59
	v_pk_mul_f32 v[50:51], v[50:51], v[62:63]
	v_pk_fma_f32 v[56:57], v[72:73], v[56:57], v[64:65]
	s_nop 0
	v_pk_fma_f32 v[52:53], v[52:53], v[60:61], v[56:57]
; __device__ __forceinline__ float shx(float v, int m, int lane) { return __int_as_float(__builtin_amdgcn_ds_bpermute((lane ^ m) << 2, __float_as_int(v))); }
; __device__ __forceinline__ float silu_f(float x) { return x * __builtin_amdgcn_rcpf(1.0f + fexp(-x)); }
; __device__ __forceinline__ void phase_dnprep(h16* Pdn, const h16* halo, const float* bd, const float* convw, const float* a_log, const float* dt_bias,
;                              h16* Tg, h16* qkg, float* gcg, float* betag, float* s2g, LAS unsigned char* ldsl, unsigned char* ldsb) {
;     ...
;                 for (int j = 0; j < 4; ++j) {
;                     const h16x8 x0 = *(const h16x8*)(raw + (i + j) * RP + seg * 128 + 16 * cp), x1 = *(const h16x8*)(raw + (i + j) * RP + seg * 128 + 16 * cp + 8);
;                     const f32x4* cwp = (const f32x4*)(cw + j * 384 + seg * 128 + 16 * cp);
;                     const f32x4 c0 = cwp[0], c1 = cwp[1], c2 = cwp[2], c3 = cwp[3];
; #pragma unroll
;                     for (int e = 0; e < 4; ++e) {
;                         y[e] += c0[e] * (float)x0[e]; y[4 + e] += c1[e] * (float)x0[4 + e];
;                         y[8 + e] += c2[e] * (float)x1[e]; y[12 + e] += c3[e] * (float)x1[4 + e];
;                     }
;                 }
; #pragma unroll
;                 for (int e = 0; e < 16; ++e) y[e] = silu_f(y[e]);
;                 float scl = bt_i;
;                 if (seg < 2) {
;                     float ss = 0.f;
; #pragma unroll
;                     for (int e = 0; e < 16; ++e) ss += y[e] * y[e];
;                     ss += shx(ss, 1, lane); ss += shx(ss, 2, lane); ss += shx(ss, 4, lane);
;                     scl = rsqrtf(ss + 1e-6f) * (seg == 0 ? 0.08838834764831845f : 1.0f);
;                 }
;                 h16x8 o0, o1;
; #pragma unroll
;                 for (int e = 0; e < 8; ++e) { o0[e] = (h16)(y[e] * scl); o1[e] = (h16)(y[8 + e] * scl); }
;                 if (seg == 0) { *(h16x8*)(qn + i * 136 + 16 * cp) = o0; *(h16x8*)(qn + i * 136 + 16 * cp + 8) = o1; }
;                 if (seg == 1) { *(h16x8*)(kn + i * 136 + 16 * cp) = o0; *(h16x8*)(kn + i * 136 + 16 * cp + 8) = o1; }
;                 gst((h16x8*)(gp + seg * 1024), o0); gst((h16x8*)(gp + seg * 1024 + 8), o1);
;             }
	v_cvt_f32_f16_e32 v60, v24
	v_cvt_f32_f16_sdwa v61, v24 dst_sel:DWORD dst_unused:UNUSED_PAD src0_sel:WORD_1
	v_cvt_f32_f16_e32 v24, v25
	v_cvt_f32_f16_sdwa v25, v25 dst_sel:DWORD dst_unused:UNUSED_PAD src0_sel:WORD_1
	v_mul_f32_e32 v56, 0xbfb8aa3b, v52
	v_pk_fma_f32 v[46:47], v[46:47], v[60:61], 0 op_sel_hi:[1,1,0]
	v_cvt_f32_f16_e32 v60, v16
	v_cvt_f32_f16_sdwa v61, v16 dst_sel:DWORD dst_unused:UNUSED_PAD src0_sel:WORD_1
	v_cvt_f32_f16_e32 v16, v17
	v_cvt_f32_f16_sdwa v17, v17 dst_sel:DWORD dst_unused:UNUSED_PAD src0_sel:WORD_1
	v_pk_fma_f32 v[24:25], v[48:49], v[24:25], 0 op_sel_hi:[1,1,0]
	v_pk_fma_f32 v[42:43], v[42:43], v[60:61], v[46:47]
	v_cvt_f32_f16_e32 v46, v4
	v_cvt_f32_f16_sdwa v47, v4 dst_sel:DWORD dst_unused:UNUSED_PAD src0_sel:WORD_1
	v_pk_fma_f32 v[16:17], v[44:45], v[16:17], v[24:25]
	v_cvt_f32_f16_e32 v24, v18
	v_cvt_f32_f16_sdwa v25, v18 dst_sel:DWORD dst_unused:UNUSED_PAD src0_sel:WORD_1
	v_pk_fma_f32 v[38:39], v[38:39], v[46:47], v[42:43]
	v_cvt_f32_f16_e32 v42, v8
	v_cvt_f32_f16_sdwa v43, v8 dst_sel:DWORD dst_unused:UNUSED_PAD src0_sel:WORD_1
	v_cvt_f32_f16_e32 v18, v19
	v_cvt_f32_f16_sdwa v19, v19 dst_sel:DWORD dst_unused:UNUSED_PAD src0_sel:WORD_1
	v_cvt_f32_f16_e32 v8, v9
	v_pk_fma_f32 v[34:35], v[34:35], v[42:43], v[38:39]
	v_cvt_f32_f16_sdwa v9, v9 dst_sel:DWORD dst_unused:UNUSED_PAD src0_sel:WORD_1
	v_mul_f32_e32 v4, 0xbfb8aa3b, v34
	v_exp_f32_e32 v4, v4
	v_mul_f32_e32 v57, 0xbfb8aa3b, v53
	v_exp_f32_e32 v56, v56
	v_exp_f32_e32 v57, v57
	v_add_f32_e32 v4, 1.0, v4
	v_rcp_f32_e32 v38, v4
	v_mul_f32_e32 v4, 0xbfb8aa3b, v35
	v_exp_f32_e32 v4, v4
	v_add_f32_e32 v56, 1.0, v56
	v_add_f32_e32 v57, 1.0, v57
	v_pk_mul_f32 v[54:55], v[54:55], v[58:59]
	v_add_f32_e32 v4, 1.0, v4
	v_rcp_f32_e32 v39, v4
	v_cvt_f32_f16_e32 v4, v5
	v_cvt_f32_f16_sdwa v5, v5 dst_sel:DWORD dst_unused:UNUSED_PAD src0_sel:WORD_1
	v_rcp_f32_e32 v56, v56
	v_pk_mul_f32 v[34:35], v[34:35], v[38:39]
	v_rcp_f32_e32 v57, v57
	v_pk_fma_f32 v[4:5], v[40:41], v[4:5], v[16:17]
	v_cvt_f32_f16_e32 v16, v26
	v_cvt_f32_f16_sdwa v17, v26 dst_sel:DWORD dst_unused:UNUSED_PAD src0_sel:WORD_1
	v_pk_fma_f32 v[4:5], v[36:37], v[8:9], v[4:5]
	v_pk_mul_f32 v[38:39], v[34:35], v[34:35]
	v_mul_f32_e32 v8, 0xbfb8aa3b, v4
	v_pk_fma_f32 v[16:17], v[28:29], v[16:17], 0 op_sel_hi:[1,1,0]
	v_mul_f32_e32 v9, 0xbfb8aa3b, v5
	v_pk_fma_f32 v[16:17], v[20:21], v[24:25], v[16:17]
	v_cvt_f32_f16_e32 v20, v6
	v_cvt_f32_f16_sdwa v21, v6 dst_sel:DWORD dst_unused:UNUSED_PAD src0_sel:WORD_1
	v_exp_f32_e32 v8, v8
	v_exp_f32_e32 v9, v9
	v_pk_mul_f32 v[58:59], v[54:55], v[54:55]
	v_pk_fma_f32 v[12:13], v[12:13], v[20:21], v[16:17]
	v_cvt_f32_f16_e32 v16, v10
	v_cvt_f32_f16_sdwa v17, v10 dst_sel:DWORD dst_unused:UNUSED_PAD src0_sel:WORD_1
	v_cvt_f32_f16_e32 v10, v11
	v_cvt_f32_f16_sdwa v11, v11 dst_sel:DWORD dst_unused:UNUSED_PAD src0_sel:WORD_1
	v_add_f32_e32 v8, 1.0, v8
	v_pk_fma_f32 v[0:1], v[0:1], v[16:17], v[12:13]
	v_cvt_f32_f16_e32 v16, v27
	v_mul_f32_e32 v6, 0xbfb8aa3b, v0
	v_exp_f32_e32 v6, v6
	v_cvt_f32_f16_sdwa v17, v27 dst_sel:DWORD dst_unused:UNUSED_PAD src0_sel:WORD_1
	v_add_f32_e32 v9, 1.0, v9
	v_rcp_f32_e32 v8, v8
	v_add_f32_e32 v6, 1.0, v6
	v_rcp_f32_e32 v12, v6
	v_mul_f32_e32 v6, 0xbfb8aa3b, v1
	v_exp_f32_e32 v6, v6
	v_pk_fma_f32 v[16:17], v[30:31], v[16:17], 0 op_sel_hi:[1,1,0]
	v_rcp_f32_e32 v9, v9
	v_pk_fma_f32 v[16:17], v[22:23], v[18:19], v[16:17]
	v_add_f32_e32 v6, 1.0, v6
	v_rcp_f32_e32 v13, v6
	v_cvt_f32_f16_e32 v6, v7
	v_cvt_f32_f16_sdwa v7, v7 dst_sel:DWORD dst_unused:UNUSED_PAD src0_sel:WORD_1
	v_pk_mul_f32 v[4:5], v[4:5], v[8:9]
	v_pk_mul_f32 v[12:13], v[0:1], v[12:13]
	v_pk_mul_f32 v[8:9], v[4:5], v[4:5]
	v_pk_fma_f32 v[6:7], v[14:15], v[6:7], v[16:17]
	v_pk_mul_f32 v[0:1], v[12:13], v[12:13]
	v_pk_fma_f32 v[2:3], v[2:3], v[10:11], v[6:7]
	v_pk_mul_f32 v[62:63], v[50:51], v[50:51]
	v_mul_f32_e32 v6, 0xbfb8aa3b, v2
	v_mul_f32_e32 v7, 0xbfb8aa3b, v3
	v_exp_f32_e32 v6, v6
	v_exp_f32_e32 v7, v7
	v_pk_mul_f32 v[52:53], v[52:53], v[56:57]
	v_add_f32_e32 v6, 1.0, v6
	v_add_f32_e32 v7, 1.0, v7
	v_rcp_f32_e32 v6, v6
	v_rcp_f32_e32 v7, v7
	v_pk_mul_f32 v[56:57], v[52:53], v[52:53]
	v_pk_mul_f32 v[10:11], v[2:3], v[6:7]
	v_add_f32_e32 v6, v38, v39
	v_add_f32_e32 v6, v8, v6
	v_add_f32_e32 v6, v9, v6
	v_add_f32_e32 v0, v0, v6
	v_pk_mul_f32 v[2:3], v[10:11], v[10:11]
	v_add_f32_e32 v0, v1, v0
	v_add_f32_e32 v0, v2, v0
	v_add_f32_e32 v0, v3, v0
	v_add_f32_e32 v0, v92, v0
	v_add_f32_e32 v0, v93, v0
	v_add_f32_e32 v0, v58, v0
	v_add_f32_e32 v0, v59, v0
	v_add_f32_e32 v0, v62, v0
	v_add_f32_e32 v0, v63, v0
	v_add_f32_e32 v0, v56, v0
	v_add_f32_e32 v0, v57, v0
	ds_bpermute_b32 v1, v104, v0
	s_waitcnt lgkmcnt(0)
	v_add_f32_e32 v0, v0, v1
	ds_bpermute_b32 v1, v103, v0
	s_waitcnt lgkmcnt(0)
	v_add_f32_e32 v0, v0, v1
	ds_bpermute_b32 v1, v102, v0
	s_waitcnt lgkmcnt(0)
	v_add_f32_e32 v0, v0, v1
	v_add_f32_e32 v0, 0x358637bd, v0
	v_cmp_gt_f32_e32 vcc, s1, v0
	v_mul_f32_e32 v1, 0x4b800000, v0
	s_movk_i32 s1, 0x1000
	v_cndmask_b32_e32 v0, v0, v1, vcc
	v_rsq_f32_e32 v0, v0
	s_nop 0
	v_mul_f32_e32 v1, 0x45800000, v0
	v_cndmask_b32_e32 v14, v0, v1, vcc
	v_pk_mul_f32 v[2:3], v[90:91], v[14:15] op_sel_hi:[1,0]
	v_pk_mul_f32 v[0:1], v[34:35], v[14:15] op_sel_hi:[1,0]
	v_cvt_pk_f16_f32 v6, v2, v3
	v_pk_mul_f32 v[2:3], v[4:5], v[14:15] op_sel_hi:[1,0]
	v_cvt_pk_f16_f32 v0, v0, v1
	v_cvt_pk_f16_f32 v1, v2, v3
	v_pk_mul_f32 v[2:3], v[54:55], v[14:15] op_sel_hi:[1,0]
	v_pk_mul_f32 v[4:5], v[50:51], v[14:15] op_sel_hi:[1,0]
	v_cvt_pk_f16_f32 v7, v2, v3
	v_pk_mul_f32 v[2:3], v[12:13], v[14:15] op_sel_hi:[1,0]
	v_cvt_pk_f16_f32 v8, v4, v5
	v_pk_mul_f32 v[4:5], v[10:11], v[14:15] op_sel_hi:[1,0]
	v_cvt_pk_f16_f32 v2, v2, v3
	v_cvt_pk_f16_f32 v3, v4, v5
	v_pk_mul_f32 v[4:5], v[52:53], v[14:15] op_sel_hi:[1,0]
	s_nop 0
	v_cvt_pk_f16_f32 v9, v4, v5
	ds_write_b128 v101, v[0:3]
	ds_write_b128 v101, v[6:9] offset:16
	global_store_dwordx4 v[86:87], v[0:3], off offset:2048
	global_store_dwordx4 v[86:87], v[6:9], off offset:2064
	ds_read_b128 v[0:3], v83 offset:5664
	ds_read_b128 v[12:15], v32 offset:2832
	ds_read_b128 v[16:19], v83 offset:4128
	ds_read_b128 v[24:27], v32 offset:2064
	ds_read_b128 v[28:31], v83 offset:2592
	ds_read_b128 v[34:37], v32 offset:1296
	ds_read_b128 v[20:23], v83 offset:1024
	ds_read_b128 v[4:7], v83 offset:1040
	ds_read_b128 v[38:41], v83 offset:1056
	ds_read_b128 v[42:45], v83 offset:1072
	ds_read_b128 v[8:11], v32 offset:512
	ds_read_b128 v[46:49], v32 offset:528
	s_waitcnt lgkmcnt(0)
; __device__ __forceinline__ float shx(float v, int m, int lane) { return __int_as_float(__builtin_amdgcn_ds_bpermute((lane ^ m) << 2, __float_as_int(v))); }
; __device__ __forceinline__ float silu_f(float x) { return x * __builtin_amdgcn_rcpf(1.0f + fexp(-x)); }
; __device__ __forceinline__ void phase_dnprep(h16* Pdn, const h16* halo, const float* bd, const float* convw, const float* a_log, const float* dt_bias,
;                              h16* Tg, h16* qkg, float* gcg, float* betag, float* s2g, LAS unsigned char* ldsl, unsigned char* ldsb) {
;     ...
;                 for (int j = 0; j < 4; ++j) {
;                     const h16x8 x0 = *(const h16x8*)(raw + (i + j) * RP + seg * 128 + 16 * cp), x1 = *(const h16x8*)(raw + (i + j) * RP + seg * 128 + 16 * cp + 8);
;                     const f32x4* cwp = (const f32x4*)(cw + j * 384 + seg * 128 + 16 * cp);
;                     const f32x4 c0 = cwp[0], c1 = cwp[1], c2 = cwp[2], c3 = cwp[3];
; #pragma unroll
;                     for (int e = 0; e < 4; ++e) {
;                         y[e] += c0[e] * (float)x0[e]; y[4 + e] += c1[e] * (float)x0[4 + e];
;                         y[8 + e] += c2[e] * (float)x1[e]; y[12 + e] += c3[e] * (float)x1[4 + e];
;                     }
;                 }
; #pragma unroll
;                 for (int e = 0; e < 16; ++e) y[e] = silu_f(y[e]);
;                 float scl = bt_i;
;                 if (seg < 2) {
;                     float ss = 0.f;
; #pragma unroll
;                     for (int e = 0; e < 16; ++e) ss += y[e] * y[e];
;                     ss += shx(ss, 1, lane); ss += shx(ss, 2, lane); ss += shx(ss, 4, lane);
;                     scl = rsqrtf(ss + 1e-6f) * (seg == 0 ? 0.08838834764831845f : 1.0f);
;                 }
;                 h16x8 o0, o1;
; #pragma unroll
;                 for (int e = 0; e < 8; ++e) { o0[e] = (h16)(y[e] * scl); o1[e] = (h16)(y[8 + e] * scl); }
;                 if (seg == 0) { *(h16x8*)(qn + i * 136 + 16 * cp) = o0; *(h16x8*)(qn + i * 136 + 16 * cp + 8) = o1; }
;                 if (seg == 1) { *(h16x8*)(kn + i * 136 + 16 * cp) = o0; *(h16x8*)(kn + i * 136 + 16 * cp + 8) = o1; }
;                 gst((h16x8*)(gp + seg * 1024), o0); gst((h16x8*)(gp + seg * 1024 + 8), o1);
	v_cvt_f32_f16_e32 v54, v34
	v_cvt_f32_f16_sdwa v55, v34 dst_sel:DWORD dst_unused:UNUSED_PAD src0_sel:WORD_1
	v_cvt_f32_f16_e32 v52, v24
	v_cvt_f32_f16_sdwa v53, v24 dst_sel:DWORD dst_unused:UNUSED_PAD src0_sel:WORD_1
	v_cvt_f32_f16_e32 v56, v46
	v_cvt_f32_f16_sdwa v57, v46 dst_sel:DWORD dst_unused:UNUSED_PAD src0_sel:WORD_1
	v_cvt_f32_f16_e32 v50, v12
	v_cvt_f32_f16_sdwa v51, v12 dst_sel:DWORD dst_unused:UNUSED_PAD src0_sel:WORD_1
	v_cvt_f32_f16_e32 v24, v35
	v_pk_fma_f32 v[38:39], v[38:39], v[56:57], 0 op_sel_hi:[1,1,0]
	v_cvt_f32_f16_e32 v34, v48
	v_pk_fma_f32 v[28:29], v[28:29], v[54:55], v[38:39]
	s_nop 0
	v_pk_fma_f32 v[16:17], v[16:17], v[52:53], v[28:29]
	v_cvt_f32_f16_e32 v28, v47
	v_pk_fma_f32 v[0:1], v[0:1], v[50:51], v[16:17]
	v_cvt_f32_f16_sdwa v29, v47 dst_sel:DWORD dst_unused:UNUSED_PAD src0_sel:WORD_1
	v_mul_f32_e32 v12, 0xbfb8aa3b, v0
	v_exp_f32_e32 v12, v12
	v_pk_fma_f32 v[28:29], v[40:41], v[28:29], 0 op_sel_hi:[1,1,0]
	v_add_f32_e32 v12, 1.0, v12
	v_rcp_f32_e32 v16, v12
	v_mul_f32_e32 v12, 0xbfb8aa3b, v1
	v_exp_f32_e32 v12, v12
	s_nop 0
	v_add_f32_e32 v12, 1.0, v12
	v_rcp_f32_e32 v17, v12
	v_cvt_f32_f16_e32 v12, v13
	v_cvt_f32_f16_sdwa v13, v13 dst_sel:DWORD dst_unused:UNUSED_PAD src0_sel:WORD_1
	v_pk_mul_f32 v[0:1], v[0:1], v[16:17]
	v_cvt_f32_f16_e32 v16, v25
	v_cvt_f32_f16_sdwa v17, v25 dst_sel:DWORD dst_unused:UNUSED_PAD src0_sel:WORD_1
	v_cvt_f32_f16_sdwa v25, v35 dst_sel:DWORD dst_unused:UNUSED_PAD src0_sel:WORD_1
	s_nop 0
	v_pk_mul_f32 v[0:1], v[88:89], v[0:1] op_sel_hi:[0,1]
	v_cvt_pk_f16_f32 v0, v0, v1
	v_cvt_f32_f16_sdwa v35, v48 dst_sel:DWORD dst_unused:UNUSED_PAD src0_sel:WORD_1
	v_pk_fma_f32 v[24:25], v[30:31], v[24:25], v[28:29]
	v_pk_fma_f32 v[34:35], v[42:43], v[34:35], 0 op_sel_hi:[1,1,0]
	v_pk_fma_f32 v[16:17], v[18:19], v[16:17], v[24:25]
	v_cvt_f32_f16_e32 v24, v36
	v_pk_fma_f32 v[2:3], v[2:3], v[12:13], v[16:17]
	ds_read_b128 v[16:19], v83 offset:5680
	ds_read_b128 v[28:31], v83 offset:4144
	ds_read_b128 v[38:41], v83 offset:2608
	v_mul_f32_e32 v1, 0xbfb8aa3b, v2
	v_exp_f32_e32 v1, v1
	v_cvt_f32_f16_sdwa v25, v36 dst_sel:DWORD dst_unused:UNUSED_PAD src0_sel:WORD_1
	v_cvt_f32_f16_e32 v42, v8
	v_cvt_f32_f16_sdwa v43, v8 dst_sel:DWORD dst_unused:UNUSED_PAD src0_sel:WORD_1
	v_add_f32_e32 v1, 1.0, v1
	v_rcp_f32_e32 v12, v1
	v_mul_f32_e32 v1, 0xbfb8aa3b, v3
	v_exp_f32_e32 v1, v1
	s_waitcnt lgkmcnt(0)
	v_pk_fma_f32 v[24:25], v[38:39], v[24:25], v[34:35]
	v_pk_fma_f32 v[20:21], v[20:21], v[42:43], 0 op_sel_hi:[1,1,0]
	v_add_f32_e32 v1, 1.0, v1
	v_rcp_f32_e32 v13, v1
	s_nop 0
	v_pk_mul_f32 v[2:3], v[2:3], v[12:13]
	s_nop 0
	v_pk_mul_f32 v[2:3], v[88:89], v[2:3] op_sel_hi:[0,1]
	v_cvt_f32_f16_e32 v12, v26
	v_cvt_f32_f16_sdwa v13, v26 dst_sel:DWORD dst_unused:UNUSED_PAD src0_sel:WORD_1
	v_cvt_pk_f16_f32 v1, v2, v3
	v_cvt_f32_f16_e32 v2, v14
	v_cvt_f32_f16_sdwa v3, v14 dst_sel:DWORD dst_unused:UNUSED_PAD src0_sel:WORD_1
	v_pk_fma_f32 v[12:13], v[28:29], v[12:13], v[24:25]
	v_cvt_f32_f16_e32 v24, v49
	v_cvt_f32_f16_sdwa v25, v49 dst_sel:DWORD dst_unused:UNUSED_PAD src0_sel:WORD_1
	v_pk_fma_f32 v[2:3], v[16:17], v[2:3], v[12:13]
	v_cvt_f32_f16_e32 v16, v37
	v_mul_f32_e32 v12, 0xbfb8aa3b, v2
	v_mul_f32_e32 v13, 0xbfb8aa3b, v3
	v_exp_f32_e32 v12, v12
	v_exp_f32_e32 v13, v13
	v_cvt_f32_f16_sdwa v17, v37 dst_sel:DWORD dst_unused:UNUSED_PAD src0_sel:WORD_1
	v_cvt_f32_f16_e32 v14, v27
	v_add_f32_e32 v12, 1.0, v12
	v_add_f32_e32 v13, 1.0, v13
	v_rcp_f32_e32 v12, v12
	v_rcp_f32_e32 v13, v13
	v_pk_fma_f32 v[24:25], v[44:45], v[24:25], 0 op_sel_hi:[1,1,0]
	v_pk_mul_f32 v[2:3], v[2:3], v[12:13]
	v_cvt_f32_f16_e32 v12, v15
	v_cvt_f32_f16_sdwa v13, v15 dst_sel:DWORD dst_unused:UNUSED_PAD src0_sel:WORD_1
	v_cvt_f32_f16_sdwa v15, v27 dst_sel:DWORD dst_unused:UNUSED_PAD src0_sel:WORD_1
	v_pk_fma_f32 v[16:17], v[40:41], v[16:17], v[24:25]
	v_pk_mul_f32 v[2:3], v[88:89], v[2:3] op_sel_hi:[0,1]
	v_cvt_pk_f16_f32 v2, v2, v3
	v_pk_fma_f32 v[14:15], v[30:31], v[14:15], v[16:17]
	s_nop 0
	v_pk_fma_f32 v[12:13], v[18:19], v[12:13], v[14:15]
	s_nop 0
	v_mul_f32_e32 v3, 0xbfb8aa3b, v12
	v_exp_f32_e32 v3, v3
	s_nop 0
	v_add_f32_e32 v3, 1.0, v3
	v_rcp_f32_e32 v14, v3
	v_mul_f32_e32 v3, 0xbfb8aa3b, v13
	v_exp_f32_e32 v3, v3
	s_nop 0
	v_add_f32_e32 v3, 1.0, v3
	v_rcp_f32_e32 v15, v3
	s_nop 0
	v_pk_mul_f32 v[12:13], v[12:13], v[14:15]
	s_nop 0
	v_pk_mul_f32 v[12:13], v[88:89], v[12:13] op_sel_hi:[0,1]
	v_cvt_pk_f16_f32 v3, v12, v13
	ds_read_b128 v[38:41], v83 offset:2560
	ds_read_b128 v[12:15], v32 offset:1280
	ds_read_b128 v[34:37], v83 offset:4096
	ds_read_b128 v[16:19], v32 offset:2048
	ds_read_b128 v[28:31], v83 offset:5632
	ds_read_b128 v[24:27], v32 offset:2816
	s_waitcnt lgkmcnt(4)
	v_cvt_f32_f16_e32 v42, v12
	v_cvt_f32_f16_sdwa v43, v12 dst_sel:DWORD dst_unused:UNUSED_PAD src0_sel:WORD_1
	v_cvt_f32_f16_e32 v12, v13
	v_cvt_f32_f16_sdwa v13, v13 dst_sel:DWORD dst_unused:UNUSED_PAD src0_sel:WORD_1
	v_pk_fma_f32 v[20:21], v[38:39], v[42:43], v[20:21]
	s_waitcnt lgkmcnt(2)
	v_cvt_f32_f16_e32 v38, v16
	v_cvt_f32_f16_sdwa v39, v16 dst_sel:DWORD dst_unused:UNUSED_PAD src0_sel:WORD_1
	v_cvt_f32_f16_e32 v16, v17
	v_cvt_f32_f16_sdwa v17, v17 dst_sel:DWORD dst_unused:UNUSED_PAD src0_sel:WORD_1
	v_pk_fma_f32 v[20:21], v[34:35], v[38:39], v[20:21]
	s_waitcnt lgkmcnt(0)
; __device__ __forceinline__ float fexp(float x) { return __builtin_amdgcn_exp2f(x * 1.4426950408889634f); }
; #define LDS_BARRIER() do { asm volatile("s_waitcnt lgkmcnt(0)" ::: "memory"); __builtin_amdgcn_s_barrier(); asm volatile("" ::: "memory"); } while (0)
; #define MFMA16(a, b, c) __builtin_amdgcn_mfma_f32_16x16x32_f16((a), (b), (c), 0, 0, 0)
; __device__ __forceinline__ void phase_dnprep(h16* Pdn, const h16* halo, const float* bd, const float* convw, const float* a_log, const float* dt_bias,
;                              h16* Tg, h16* qkg, float* gcg, float* betag, float* s2g, LAS unsigned char* ldsl, unsigned char* ldsb) {
;     ...
;                 for (int e = 0; e < 8; ++e) { o0[e] = (h16)(y[e] * scl); o1[e] = (h16)(y[8 + e] * scl); }
;                 if (seg == 0) { *(h16x8*)(qn + i * 136 + 16 * cp) = o0; *(h16x8*)(qn + i * 136 + 16 * cp + 8) = o1; }
;                 if (seg == 1) { *(h16x8*)(kn + i * 136 + 16 * cp) = o0; *(h16x8*)(kn + i * 136 + 16 * cp + 8) = o1; }
;                 gst((h16x8*)(gp + seg * 1024), o0); gst((h16x8*)(gp + seg * 1024 + 8), o1);
;             }
;         }
;         LDS_BARRIER();
; #pragma unroll
;         for (int idx0 = 0; idx0 < 4; ++idx0) {
;             const int idx = w + 8 * idx0;
;             const int isqk = idx >> 4, ti = (idx >> 2) & 3, tj = idx & 3;
;             f32x4 acc = {0.f, 0.f, 0.f, 0.f};
;             if (tj <= ti) {
;                 const h16* As = isqk ? qn : kn;
; #pragma unroll
;                 for (int kk = 0; kk < 4; ++kk) {
;                     const h16x8 a = *(const h16x8*)(As + (16 * ti + fr) * 136 + 32 * kk + 8 * g);
;                     const h16x8 bb = *(const h16x8*)(kn + (16 * tj + fr) * 136 + 32 * kk + 8 * g);
;                     acc = MFMA16(a, bb, acc);
;                 }
;             }
; #pragma unroll
;             for (int rg = 0; rg < 4; ++rg) {
;                 const int i = 16 * ti + 4 * g + rg, j = 16 * tj + fr;
;                 const float dec = fexp(fminf(gcs[i] - gcs[j], 0.f));
;                 if (!isqk) Mm[i * 68 + j] = (j < i) ? acc[rg] * bts[i] * dec : 0.f;
	v_cvt_f32_f16_e32 v34, v24
	v_cvt_f32_f16_sdwa v35, v24 dst_sel:DWORD dst_unused:UNUSED_PAD src0_sel:WORD_1
	v_cvt_f32_f16_e32 v38, v10
	v_cvt_f32_f16_sdwa v39, v10 dst_sel:DWORD dst_unused:UNUSED_PAD src0_sel:WORD_1
	v_cvt_f32_f16_e32 v24, v14
	v_pk_fma_f32 v[20:21], v[28:29], v[34:35], v[20:21]
	v_pk_fma_f32 v[4:5], v[4:5], v[38:39], 0 op_sel_hi:[1,1,0]
	v_mul_f32_e32 v8, 0xbfb8aa3b, v20
	v_exp_f32_e32 v8, v8
	s_nop 0
	v_add_f32_e32 v8, 1.0, v8
	v_rcp_f32_e32 v28, v8
	v_mul_f32_e32 v8, 0xbfb8aa3b, v21
	v_exp_f32_e32 v8, v8
	s_nop 0
	v_add_f32_e32 v8, 1.0, v8
	v_rcp_f32_e32 v29, v8
	s_nop 0
	v_pk_mul_f32 v[20:21], v[20:21], v[28:29]
	s_nop 0
	v_pk_mul_f32 v[20:21], v[88:89], v[20:21] op_sel_hi:[0,1]
	v_cvt_pk_f16_f32 v8, v20, v21
	v_cvt_f32_f16_e32 v20, v9
	v_cvt_f32_f16_sdwa v21, v9 dst_sel:DWORD dst_unused:UNUSED_PAD src0_sel:WORD_1
	v_pk_fma_f32 v[20:21], v[22:23], v[20:21], 0 op_sel_hi:[1,1,0]
	s_nop 0
	v_pk_fma_f32 v[12:13], v[40:41], v[12:13], v[20:21]
	s_nop 0
	v_pk_fma_f32 v[12:13], v[36:37], v[16:17], v[12:13]
	v_cvt_f32_f16_e32 v16, v25
	v_cvt_f32_f16_sdwa v17, v25 dst_sel:DWORD dst_unused:UNUSED_PAD src0_sel:WORD_1
	v_cvt_f32_f16_sdwa v25, v14 dst_sel:DWORD dst_unused:UNUSED_PAD src0_sel:WORD_1
	v_cvt_f32_f16_e32 v14, v15
	v_cvt_f32_f16_sdwa v15, v15 dst_sel:DWORD dst_unused:UNUSED_PAD src0_sel:WORD_1
	v_pk_fma_f32 v[12:13], v[30:31], v[16:17], v[12:13]
	ds_read_b128 v[20:23], v83 offset:5648
	ds_read_b128 v[28:31], v83 offset:4112
	ds_read_b128 v[34:37], v83 offset:2576
	v_mul_f32_e32 v9, 0xbfb8aa3b, v12
	v_exp_f32_e32 v9, v9
	s_waitcnt lgkmcnt(0)
	v_pk_fma_f32 v[4:5], v[34:35], v[24:25], v[4:5]
	v_add_f32_e32 v9, 1.0, v9
	v_rcp_f32_e32 v16, v9
	v_mul_f32_e32 v9, 0xbfb8aa3b, v13
	v_exp_f32_e32 v9, v9
	s_nop 0
	v_add_f32_e32 v9, 1.0, v9
	v_rcp_f32_e32 v17, v9
	s_nop 0
	v_pk_mul_f32 v[12:13], v[12:13], v[16:17]
	s_nop 0
	v_pk_mul_f32 v[12:13], v[88:89], v[12:13] op_sel_hi:[0,1]
	v_cvt_f32_f16_e32 v16, v18
	v_cvt_f32_f16_sdwa v17, v18 dst_sel:DWORD dst_unused:UNUSED_PAD src0_sel:WORD_1
	v_cvt_pk_f16_f32 v9, v12, v13
	v_cvt_f32_f16_e32 v12, v26
	v_cvt_f32_f16_sdwa v13, v26 dst_sel:DWORD dst_unused:UNUSED_PAD src0_sel:WORD_1
	v_pk_fma_f32 v[4:5], v[28:29], v[16:17], v[4:5]
	v_cvt_f32_f16_e32 v16, v11
	v_cvt_f32_f16_sdwa v17, v11 dst_sel:DWORD dst_unused:UNUSED_PAD src0_sel:WORD_1
	v_pk_fma_f32 v[4:5], v[20:21], v[12:13], v[4:5]
	v_pk_fma_f32 v[6:7], v[6:7], v[16:17], 0 op_sel_hi:[1,1,0]
	v_mul_f32_e32 v10, 0xbfb8aa3b, v4
	v_exp_f32_e32 v10, v10
	v_pk_fma_f32 v[6:7], v[36:37], v[14:15], v[6:7]
	v_add_f32_e32 v10, 1.0, v10
	v_rcp_f32_e32 v12, v10
	v_mul_f32_e32 v10, 0xbfb8aa3b, v5
	v_exp_f32_e32 v10, v10
	s_nop 0
	v_add_f32_e32 v10, 1.0, v10
	v_rcp_f32_e32 v13, v10
	s_nop 0
	v_pk_mul_f32 v[4:5], v[4:5], v[12:13]
	s_nop 0
	v_pk_mul_f32 v[4:5], v[88:89], v[4:5] op_sel_hi:[0,1]
	v_cvt_f32_f16_e32 v12, v19
	v_cvt_f32_f16_sdwa v13, v19 dst_sel:DWORD dst_unused:UNUSED_PAD src0_sel:WORD_1
	v_cvt_pk_f16_f32 v10, v4, v5
	v_cvt_f32_f16_e32 v4, v27
	v_cvt_f32_f16_sdwa v5, v27 dst_sel:DWORD dst_unused:UNUSED_PAD src0_sel:WORD_1
	v_pk_fma_f32 v[6:7], v[30:31], v[12:13], v[6:7]
	s_nop 0
	v_pk_fma_f32 v[4:5], v[22:23], v[4:5], v[6:7]
	s_nop 0
	v_mul_f32_e32 v6, 0xbfb8aa3b, v4
	v_mul_f32_e32 v7, 0xbfb8aa3b, v5
	v_exp_f32_e32 v6, v6
	v_exp_f32_e32 v7, v7
	v_or_b32_e32 v22, s76, v100
	v_add_f32_e32 v6, 1.0, v6
	v_add_f32_e32 v7, 1.0, v7
	v_rcp_f32_e32 v6, v6
	v_rcp_f32_e32 v7, v7
	s_nop 0
	v_pk_mul_f32 v[4:5], v[4:5], v[6:7]
	s_nop 0
	v_pk_mul_f32 v[4:5], v[88:89], v[4:5] op_sel_hi:[0,1]
	v_cvt_pk_f16_f32 v11, v4, v5
	v_add_co_u32_e32 v4, vcc, s1, v86
	s_nop 1
	v_addc_co_u32_e32 v5, vcc, 0, v87, vcc
	global_store_dwordx4 v[4:5], v[8:11], off
	global_store_dwordx4 v[4:5], v[0:3], off offset:16
	s_waitcnt lgkmcnt(0)
	s_barrier
	s_and_b64 vcc, exec, s[28:29]
	v_mul_u32_u24_e32 v0, 0x110, v22
	v_and_b32_e32 v2, 48, v99
	v_lshlrev_b32_e32 v1, 3, v84
	v_add3_u32 v23, s0, v0, v2
	v_or_b32_e32 v2, s95, v100
	v_mov_b32_e32 v0, 0
	v_lshlrev_b32_e32 v24, 1, v1
	v_mul_u32_u24_e32 v25, 0x110, v2
	v_mov_b32_e32 v1, 0
	v_mov_b32_e32 v2, 0
	v_mov_b32_e32 v3, 0
	ds_read_b128 v[236:239], v23
	ds_read_b128 v[240:243], v23 offset:64
	ds_read_b128 v[244:247], v23 offset:128
	ds_read_b128 v[248:251], v23 offset:192
	v_lshlrev_b32_e32 v204, 2, v84
	v_lshlrev_b32_e32 v207, 2, v22
	v_or_b32_e32 v205, s95, v204
	v_or_b32_e32 v206, s97, v204
	v_lshlrev_b32_e32 v205, 2, v205
	v_lshlrev_b32_e32 v206, 2, v206
	v_add_u32_e32 v205, 0x27600, v205
	v_add_u32_e32 v206, 0x27600, v206
	v_add_u32_e32 v207, 0x27600, v207
	ds_read_b128 v[208:211], v205
	ds_read_b128 v[212:215], v205 offset:256
	ds_read_b32 v224, v207
	ds_read_b128 v[216:219], v206
	ds_read_b128 v[220:223], v206 offset:256
	s_cbranch_vccz .LBB0_356
	v_add3_u32 v12, s94, v25, v24
	ds_read_b128 v[228:231], v12
	ds_read_b128 v[232:235], v12 offset:64
	ds_read_b128 v[102:105], v12 offset:128
	ds_read_b128 v[106:109], v12 offset:192
	s_waitcnt lgkmcnt(3)
	v_mfma_f32_16x16x32_f16 v[0:3], v[228:231], v[236:239], 0
	s_waitcnt lgkmcnt(2)
	v_mfma_f32_16x16x32_f16 v[0:3], v[232:235], v[240:243], v[0:3]
	s_waitcnt lgkmcnt(1)
	v_mfma_f32_16x16x32_f16 v[0:3], v[102:105], v[244:247], v[0:3]
	s_waitcnt lgkmcnt(0)
	v_mfma_f32_16x16x32_f16 v[0:3], v[106:109], v[248:251], v[0:3]
.LBB0_356:
	s_waitcnt lgkmcnt(0)
	v_lshlrev_b32_e32 v14, 2, v84
	v_lshlrev_b32_e32 v5, 2, v22
	s_add_i32 s0, 0, 0x27600
	v_or_b32_e32 v26, s95, v14
	v_add_u32_e32 v4, s0, v5
	v_lshl_add_u32 v8, v26, 2, s0
	v_mov_b32_e32 v8, v208
	v_mov_b32_e32 v4, v224
	v_readlane_b32 s4, v255, 27
	v_lshlrev_b32_e32 v32, 1, v22
	v_readlane_b32 s5, v255, 28
	s_and_b64 vcc, exec, s[30:31]
	s_waitcnt lgkmcnt(0)
	v_sub_f32_e32 v8, v8, v4
	v_min_f32_e32 v8, 0, v8
	v_mul_f32_e32 v8, 0x3fb8aa3b, v8
	v_exp_f32_e32 v27, v8
	v_or_b32_e32 v8, s26, v26
	v_lshl_add_u64 v[6:7], s[4:5], 0, v[32:33]
	s_mov_b64 s[4:5], -1
	v_cmp_le_u32_e64 s[0:1], v22, v26
	v_lshlrev_b32_e32 v32, 6, v8
	s_cbranch_vccz .LBB0_358
	v_fma_mixlo_f16 v10, v0, v27, 0
	v_lshl_add_u64 v[8:9], v[32:33], 1, v[6:7]
	v_cndmask_b32_e64 v10, 0, v10, s[0:1]
	global_store_short v[8:9], v10, off
	s_mov_b64 s[4:5], 0
.LBB0_358:
	s_add_i32 s3, 0, 0x21a00
	s_andn2_b64 vcc, exec, s[4:5]
	v_add_u32_e32 v5, s3, v5
	s_cbranch_vccnz .LBB0_362
	v_cmp_lt_u32_e32 vcc, v22, v26
	v_mov_b32_e32 v8, 0
	s_and_saveexec_b64 s[0:1], vcc
	s_cbranch_execz .LBB0_361
	v_lshl_add_u32 v8, v26, 2, 0
	v_add_u32_e32 v8, 0x27700, v8
	v_mov_b32_e32 v8, v212
	s_waitcnt lgkmcnt(0)
	v_mul_f32_e32 v0, v0, v8
	v_mul_f32_e32 v8, v27, v0

; __device__ __forceinline__ float fexp(float x) { return __builtin_amdgcn_exp2f(x * 1.4426950408889634f); }
; __device__ __forceinline__ void phase_dnprep(h16* Pdn, const h16* halo, const float* bd, const float* convw, const float* a_log, const float* dt_bias,
;                              h16* Tg, h16* qkg, float* gcg, float* betag, float* s2g, LAS unsigned char* ldsl, unsigned char* ldsb) {
;     ...
; #pragma unroll
;             for (int rg = 0; rg < 4; ++rg) {
;                 const int i = 16 * ti + 4 * g + rg, j = 16 * tj + fr;
;                 const float dec = fexp(fminf(gcs[i] - gcs[j], 0.f));
;                 if (!isqk) Mm[i * 68 + j] = (j < i) ? acc[rg] * bts[i] * dec : 0.f;
;                 else gst(qkg + (bh0 + i) * 64 + j, (h16)((j <= i) ? acc[rg] * dec : 0.f));
.LBB0_362:
	v_or_b32_e32 v28, 1, v26
	v_lshl_add_u32 v0, v28, 2, 0
	v_add_u32_e32 v8, 0x27600, v0
	v_mov_b32_e32 v8, v209
	v_cndmask_b32_e64 v9, 0, 1, s[30:31]
	s_mov_b64 s[6:7], -1
	v_cmp_ne_u32_e64 s[0:1], 1, v9
	s_andn2_b64 vcc, exec, s[30:31]
	s_waitcnt lgkmcnt(0)
	v_sub_f32_e32 v8, v8, v4
	v_min_f32_e32 v8, 0, v8
	v_mul_f32_e32 v8, 0x3fb8aa3b, v8
	v_exp_f32_e32 v29, v8
	v_or_b32_e32 v8, s26, v28
	v_cmp_le_u32_e64 s[4:5], v22, v28
	v_lshlrev_b32_e32 v8, 6, v8
	s_cbranch_vccnz .LBB0_364
	v_mov_b32_e32 v9, v33
	v_lshl_add_u64 v[10:11], v[8:9], 1, v[6:7]
	v_fma_mixlo_f16 v9, v1, v29, 0
	v_cndmask_b32_e64 v9, 0, v9, s[4:5]
	s_mov_b64 s[6:7], 0
	global_store_short v[10:11], v9, off
.LBB0_364:
	s_andn2_b64 vcc, exec, s[6:7]
	s_cbranch_vccnz .LBB0_368
	v_cmp_le_u32_e32 vcc, v22, v26
	v_mov_b32_e32 v9, 0
	s_and_saveexec_b64 s[4:5], vcc
	s_cbranch_execz .LBB0_367
	v_add_u32_e32 v0, 0x27700, v0
	v_mov_b32_e32 v0, v213
	s_waitcnt lgkmcnt(0)
	v_mul_f32_e32 v0, v1, v0
	v_mul_f32_e32 v9, v29, v0

; __device__ __forceinline__ float fexp(float x) { return __builtin_amdgcn_exp2f(x * 1.4426950408889634f); }
; __device__ __forceinline__ void phase_dnprep(h16* Pdn, const h16* halo, const float* bd, const float* convw, const float* a_log, const float* dt_bias,
;                              h16* Tg, h16* qkg, float* gcg, float* betag, float* s2g, LAS unsigned char* ldsl, unsigned char* ldsb) {
;     ...
; #pragma unroll
;             for (int rg = 0; rg < 4; ++rg) {
;                 const int i = 16 * ti + 4 * g + rg, j = 16 * tj + fr;
;                 const float dec = fexp(fminf(gcs[i] - gcs[j], 0.f));
;                 if (!isqk) Mm[i * 68 + j] = (j < i) ? acc[rg] * bts[i] * dec : 0.f;
;                 else gst(qkg + (bh0 + i) * 64 + j, (h16)((j <= i) ? acc[rg] * dec : 0.f));
.LBB0_368:
	v_or_b32_e32 v30, 2, v26
	v_lshl_add_u32 v0, v30, 2, 0
	v_add_u32_e32 v1, 0x27600, v0
	v_mov_b32_e32 v1, v210
	s_mov_b64 s[6:7], -1
	s_and_b64 vcc, exec, s[0:1]
	v_cmp_le_u32_e64 s[4:5], v22, v30
	s_waitcnt lgkmcnt(0)
	v_sub_f32_e32 v1, v1, v4
	v_min_f32_e32 v1, 0, v1
	v_mul_f32_e32 v1, 0x3fb8aa3b, v1
	v_exp_f32_e32 v31, v1
	v_or_b32_e32 v1, s26, v30
	v_lshlrev_b32_e32 v10, 6, v1
	s_cbranch_vccnz .LBB0_370
	v_mov_b32_e32 v11, v33
	v_fma_mixlo_f16 v1, v2, v31, 0
	v_lshl_add_u64 v[12:13], v[10:11], 1, v[6:7]
	v_cndmask_b32_e64 v1, 0, v1, s[4:5]
	s_mov_b64 s[6:7], 0
	global_store_short v[12:13], v1, off
.LBB0_370:
	s_andn2_b64 vcc, exec, s[6:7]
	s_cbranch_vccnz .LBB0_374
	v_cmp_lt_u32_e32 vcc, v22, v30
	v_mov_b32_e32 v1, 0
	s_and_saveexec_b64 s[4:5], vcc
	s_cbranch_execz .LBB0_373
	v_add_u32_e32 v0, 0x27700, v0
	v_mov_b32_e32 v0, v214
	s_waitcnt lgkmcnt(0)
	v_mul_f32_e32 v0, v2, v0
	v_mul_f32_e32 v1, v31, v0

; __device__ __forceinline__ float fexp(float x) { return __builtin_amdgcn_exp2f(x * 1.4426950408889634f); }
; __device__ __forceinline__ void phase_dnprep(h16* Pdn, const h16* halo, const float* bd, const float* convw, const float* a_log, const float* dt_bias,
;                              h16* Tg, h16* qkg, float* gcg, float* betag, float* s2g, LAS unsigned char* ldsl, unsigned char* ldsb) {
;     ...
; #pragma unroll
;             for (int rg = 0; rg < 4; ++rg) {
;                 const int i = 16 * ti + 4 * g + rg, j = 16 * tj + fr;
;                 const float dec = fexp(fminf(gcs[i] - gcs[j], 0.f));
;                 if (!isqk) Mm[i * 68 + j] = (j < i) ? acc[rg] * bts[i] * dec : 0.f;
;                 else gst(qkg + (bh0 + i) * 64 + j, (h16)((j <= i) ? acc[rg] * dec : 0.f));
.LBB0_374:
	v_or_b32_e32 v34, 3, v26
	v_lshl_add_u32 v0, v34, 2, 0
	v_add_u32_e32 v1, 0x27600, v0
	v_mov_b32_e32 v1, v211
	s_mov_b64 s[4:5], -1
	s_and_b64 vcc, exec, s[0:1]
	v_cmp_le_u32_e64 s[0:1], v22, v34
	s_waitcnt lgkmcnt(0)
	v_sub_f32_e32 v1, v1, v4
	v_min_f32_e32 v1, 0, v1
	v_mul_f32_e32 v1, 0x3fb8aa3b, v1
	v_exp_f32_e32 v35, v1
	v_or_b32_e32 v1, s26, v34
	v_lshlrev_b32_e32 v12, 6, v1
	s_cbranch_vccnz .LBB0_376
	v_mov_b32_e32 v13, v33
	v_fma_mixlo_f16 v1, v3, v35, 0
	v_lshl_add_u64 v[16:17], v[12:13], 1, v[6:7]
	v_cndmask_b32_e64 v1, 0, v1, s[0:1]
	s_mov_b64 s[4:5], 0
	global_store_short v[16:17], v1, off
.LBB0_376:
	s_andn2_b64 vcc, exec, s[4:5]
	s_cbranch_vccnz .LBB0_380
	v_cmp_lt_u32_e32 vcc, v22, v34
	v_mov_b32_e32 v1, 0
	s_and_saveexec_b64 s[0:1], vcc
	s_cbranch_execz .LBB0_379
	v_add_u32_e32 v0, 0x27700, v0
	v_mov_b32_e32 v0, v215
	s_waitcnt lgkmcnt(0)
	v_mul_f32_e32 v0, v3, v0
	v_mul_f32_e32 v1, v35, v0

; __device__ __forceinline__ float fexp(float x) { return __builtin_amdgcn_exp2f(x * 1.4426950408889634f); }
; #define MFMA16(a, b, c) __builtin_amdgcn_mfma_f32_16x16x32_f16((a), (b), (c), 0, 0, 0)
; __device__ __forceinline__ void phase_dnprep(h16* Pdn, const h16* halo, const float* bd, const float* convw, const float* a_log, const float* dt_bias,
;                              h16* Tg, h16* qkg, float* gcg, float* betag, float* s2g, LAS unsigned char* ldsl, unsigned char* ldsb) {
;     ...
;         for (int idx0 = 0; idx0 < 4; ++idx0) {
;             const int idx = w + 8 * idx0;
;             const int isqk = idx >> 4, ti = (idx >> 2) & 3, tj = idx & 3;
;             f32x4 acc = {0.f, 0.f, 0.f, 0.f};
;             if (tj <= ti) {
;                 const h16* As = isqk ? qn : kn;
; #pragma unroll
;                 for (int kk = 0; kk < 4; ++kk) {
;                     const h16x8 a = *(const h16x8*)(As + (16 * ti + fr) * 136 + 32 * kk + 8 * g);
;                     const h16x8 bb = *(const h16x8*)(kn + (16 * tj + fr) * 136 + 32 * kk + 8 * g);
;                     acc = MFMA16(a, bb, acc);
;                 }
;             }
; #pragma unroll
;             for (int rg = 0; rg < 4; ++rg) {
;                 const int i = 16 * ti + 4 * g + rg, j = 16 * tj + fr;
;                 const float dec = fexp(fminf(gcs[i] - gcs[j], 0.f));
;                 if (!isqk) Mm[i * 68 + j] = (j < i) ? acc[rg] * bts[i] * dec : 0.f;
;                 else gst(qkg + (bh0 + i) * 64 + j, (h16)((j <= i) ? acc[rg] * dec : 0.f));
.LBB0_380:
	v_cndmask_b32_e64 v1, 0, 1, s[88:89]
	v_cmp_ne_u32_e64 s[4:5], 1, v1
	v_or_b32_e32 v1, s97, v100
	v_mov_b32_e32 v0, 0
	s_andn2_b64 vcc, exec, s[88:89]
	v_mul_u32_u24_e32 v36, 0x110, v1
	v_mov_b32_e32 v1, 0
	v_mov_b32_e32 v2, 0
	v_mov_b32_e32 v3, 0
	s_cbranch_vccnz .LBB0_382
	v_add3_u32 v9, s96, v36, v24
	ds_read_b128 v[228:231], v9
	ds_read_b128 v[232:235], v9 offset:64
	ds_read_b128 v[102:105], v9 offset:128
	ds_read_b128 v[106:109], v9 offset:192
	s_waitcnt lgkmcnt(3)
	v_mfma_f32_16x16x32_f16 v[0:3], v[228:231], v[236:239], 0
	s_waitcnt lgkmcnt(2)
	v_mfma_f32_16x16x32_f16 v[0:3], v[232:235], v[240:243], v[0:3]
	s_waitcnt lgkmcnt(1)
	v_mfma_f32_16x16x32_f16 v[0:3], v[102:105], v[244:247], v[0:3]
	s_waitcnt lgkmcnt(0)
	v_mfma_f32_16x16x32_f16 v[0:3], v[106:109], v[248:251], v[0:3]
.LBB0_382:
	v_or_b32_e32 v37, s97, v14
	v_lshl_add_u32 v9, v37, 2, 0
	v_add_u32_e32 v11, 0x27600, v9
	v_mov_b32_e32 v11, v216
	v_cndmask_b32_e64 v13, 0, 1, s[18:19]
	s_mov_b64 s[20:21], -1
	v_cmp_ne_u32_e64 s[6:7], 1, v13
	s_andn2_b64 vcc, exec, s[18:19]
	s_waitcnt lgkmcnt(0)
	v_sub_f32_e32 v11, v11, v4
	v_min_f32_e32 v11, 0, v11
	v_mul_f32_e32 v11, 0x3fb8aa3b, v11
	v_exp_f32_e32 v38, v11
	v_or_b32_e32 v11, s26, v37
	v_cmp_le_u32_e64 s[0:1], v22, v37
	v_lshlrev_b32_e32 v14, 6, v11
	s_cbranch_vccnz .LBB0_384
	v_mov_b32_e32 v15, v33
	v_fma_mixlo_f16 v11, v0, v38, 0
	v_lshl_add_u64 v[16:17], v[14:15], 1, v[6:7]
	v_cndmask_b32_e64 v11, 0, v11, s[0:1]
	s_mov_b64 s[20:21], 0
	global_store_short v[16:17], v11, off
.LBB0_384:
	s_andn2_b64 vcc, exec, s[20:21]
	s_cbranch_vccnz .LBB0_388
	v_cmp_lt_u32_e32 vcc, v22, v37
	v_mov_b32_e32 v11, 0
	s_and_saveexec_b64 s[0:1], vcc
	s_cbranch_execz .LBB0_387
	v_add_u32_e32 v9, 0x27700, v9
	v_mov_b32_e32 v9, v220
	s_waitcnt lgkmcnt(0)
	v_mul_f32_e32 v0, v0, v9
	v_mul_f32_e32 v11, v38, v0

; __device__ __forceinline__ float fexp(float x) { return __builtin_amdgcn_exp2f(x * 1.4426950408889634f); }
; __device__ __forceinline__ void phase_dnprep(h16* Pdn, const h16* halo, const float* bd, const float* convw, const float* a_log, const float* dt_bias,
;                              h16* Tg, h16* qkg, float* gcg, float* betag, float* s2g, LAS unsigned char* ldsl, unsigned char* ldsb) {
;     ...
; #pragma unroll
;             for (int rg = 0; rg < 4; ++rg) {
;                 const int i = 16 * ti + 4 * g + rg, j = 16 * tj + fr;
;                 const float dec = fexp(fminf(gcs[i] - gcs[j], 0.f));
;                 if (!isqk) Mm[i * 68 + j] = (j < i) ? acc[rg] * bts[i] * dec : 0.f;
;                 else gst(qkg + (bh0 + i) * 64 + j, (h16)((j <= i) ? acc[rg] * dec : 0.f));
.LBB0_388:
	v_or_b32_e32 v39, 1, v37
	v_lshl_add_u32 v0, v39, 2, 0
	v_add_u32_e32 v9, 0x27600, v0
	v_mov_b32_e32 v9, v217
	s_mov_b64 s[20:21], -1
	s_and_b64 vcc, exec, s[6:7]
	v_cmp_le_u32_e64 s[0:1], v22, v39
	s_waitcnt lgkmcnt(0)
	v_sub_f32_e32 v9, v9, v4
	v_min_f32_e32 v9, 0, v9
	v_mul_f32_e32 v9, 0x3fb8aa3b, v9
	v_exp_f32_e32 v40, v9
	v_or_b32_e32 v9, s26, v39
	v_lshlrev_b32_e32 v16, 6, v9
	s_cbranch_vccnz .LBB0_390
	v_mov_b32_e32 v17, v33
	v_fma_mixlo_f16 v9, v1, v40, 0
	v_lshl_add_u64 v[18:19], v[16:17], 1, v[6:7]
	v_cndmask_b32_e64 v9, 0, v9, s[0:1]
	s_mov_b64 s[20:21], 0
	global_store_short v[18:19], v9, off
.LBB0_390:
	s_andn2_b64 vcc, exec, s[20:21]
	s_cbranch_vccnz .LBB0_394
	v_cmp_le_u32_e32 vcc, v22, v37
	v_mov_b32_e32 v9, 0
	s_and_saveexec_b64 s[0:1], vcc
	s_cbranch_execz .LBB0_393
	v_add_u32_e32 v0, 0x27700, v0
	v_mov_b32_e32 v0, v221
	s_waitcnt lgkmcnt(0)
	v_mul_f32_e32 v0, v1, v0
	v_mul_f32_e32 v9, v40, v0

; __device__ __forceinline__ float fexp(float x) { return __builtin_amdgcn_exp2f(x * 1.4426950408889634f); }
; __device__ __forceinline__ void phase_dnprep(h16* Pdn, const h16* halo, const float* bd, const float* convw, const float* a_log, const float* dt_bias,
;                              h16* Tg, h16* qkg, float* gcg, float* betag, float* s2g, LAS unsigned char* ldsl, unsigned char* ldsb) {
;     ...
; #pragma unroll
;             for (int rg = 0; rg < 4; ++rg) {
;                 const int i = 16 * ti + 4 * g + rg, j = 16 * tj + fr;
;                 const float dec = fexp(fminf(gcs[i] - gcs[j], 0.f));
;                 if (!isqk) Mm[i * 68 + j] = (j < i) ? acc[rg] * bts[i] * dec : 0.f;
;                 else gst(qkg + (bh0 + i) * 64 + j, (h16)((j <= i) ? acc[rg] * dec : 0.f));
.LBB0_394:
	v_or_b32_e32 v41, 2, v37
	v_lshl_add_u32 v0, v41, 2, 0
	v_add_u32_e32 v1, 0x27600, v0
	v_mov_b32_e32 v1, v218
	s_mov_b64 s[20:21], -1
	s_and_b64 vcc, exec, s[6:7]
	v_cmp_le_u32_e64 s[0:1], v22, v41
	s_waitcnt lgkmcnt(0)
	v_sub_f32_e32 v1, v1, v4
	v_min_f32_e32 v1, 0, v1
	v_mul_f32_e32 v1, 0x3fb8aa3b, v1
	v_exp_f32_e32 v42, v1
	v_or_b32_e32 v1, s26, v41
	v_lshlrev_b32_e32 v18, 6, v1
	s_cbranch_vccnz .LBB0_396
	v_mov_b32_e32 v19, v33
	v_fma_mixlo_f16 v1, v2, v42, 0
	v_lshl_add_u64 v[20:21], v[18:19], 1, v[6:7]
	v_cndmask_b32_e64 v1, 0, v1, s[0:1]
	s_mov_b64 s[20:21], 0
	global_store_short v[20:21], v1, off
.LBB0_396:
	s_andn2_b64 vcc, exec, s[20:21]
	s_cbranch_vccnz .LBB0_400
	v_cmp_lt_u32_e32 vcc, v22, v41
	v_mov_b32_e32 v1, 0
	s_and_saveexec_b64 s[0:1], vcc
	s_cbranch_execz .LBB0_399
	v_add_u32_e32 v0, 0x27700, v0
	v_mov_b32_e32 v0, v222
	s_waitcnt lgkmcnt(0)
	v_mul_f32_e32 v0, v2, v0
	v_mul_f32_e32 v1, v42, v0

; __device__ __forceinline__ float fexp(float x) { return __builtin_amdgcn_exp2f(x * 1.4426950408889634f); }
; __device__ __forceinline__ void phase_dnprep(h16* Pdn, const h16* halo, const float* bd, const float* convw, const float* a_log, const float* dt_bias,
;                              h16* Tg, h16* qkg, float* gcg, float* betag, float* s2g, LAS unsigned char* ldsl, unsigned char* ldsb) {
;     ...
; #pragma unroll
;             for (int rg = 0; rg < 4; ++rg) {
;                 const int i = 16 * ti + 4 * g + rg, j = 16 * tj + fr;
;                 const float dec = fexp(fminf(gcs[i] - gcs[j], 0.f));
;                 if (!isqk) Mm[i * 68 + j] = (j < i) ? acc[rg] * bts[i] * dec : 0.f;
;                 else gst(qkg + (bh0 + i) * 64 + j, (h16)((j <= i) ? acc[rg] * dec : 0.f));
.LBB0_400:
	v_or_b32_e32 v43, 3, v37
	v_lshl_add_u32 v0, v43, 2, 0
	v_add_u32_e32 v1, 0x27600, v0
	v_mov_b32_e32 v1, v219
	s_mov_b64 s[20:21], -1
	s_and_b64 vcc, exec, s[6:7]
	v_cmp_le_u32_e64 s[0:1], v22, v43
	s_waitcnt lgkmcnt(0)
	v_sub_f32_e32 v1, v1, v4
	v_min_f32_e32 v1, 0, v1
	v_mul_f32_e32 v1, 0x3fb8aa3b, v1
	v_exp_f32_e32 v44, v1
	v_or_b32_e32 v1, s26, v43
	v_lshlrev_b32_e32 v20, 6, v1
	s_cbranch_vccnz .LBB0_402
	v_mov_b32_e32 v21, v33
	v_fma_mixlo_f16 v1, v3, v44, 0
	v_lshl_add_u64 v[46:47], v[20:21], 1, v[6:7]
	v_cndmask_b32_e64 v1, 0, v1, s[0:1]
	s_mov_b64 s[20:21], 0
	global_store_short v[46:47], v1, off
.LBB0_402:
	s_andn2_b64 vcc, exec, s[20:21]
	s_cbranch_vccnz .LBB0_406
	v_cmp_lt_u32_e32 vcc, v22, v43
	v_mov_b32_e32 v1, 0
	s_and_saveexec_b64 s[0:1], vcc
	s_cbranch_execz .LBB0_405
	v_add_u32_e32 v0, 0x27700, v0
	v_mov_b32_e32 v0, v223
	s_waitcnt lgkmcnt(0)
	v_mul_f32_e32 v0, v3, v0
	v_mul_f32_e32 v1, v44, v0

; __device__ __forceinline__ float fexp(float x) { return __builtin_amdgcn_exp2f(x * 1.4426950408889634f); }
; #define MFMA16(a, b, c) __builtin_amdgcn_mfma_f32_16x16x32_f16((a), (b), (c), 0, 0, 0)
; __device__ __forceinline__ void phase_dnprep(h16* Pdn, const h16* halo, const float* bd, const float* convw, const float* a_log, const float* dt_bias,
;                              h16* Tg, h16* qkg, float* gcg, float* betag, float* s2g, LAS unsigned char* ldsl, unsigned char* ldsb) {
;     ...
;         for (int idx0 = 0; idx0 < 4; ++idx0) {
;             const int idx = w + 8 * idx0;
;             const int isqk = idx >> 4, ti = (idx >> 2) & 3, tj = idx & 3;
;             f32x4 acc = {0.f, 0.f, 0.f, 0.f};
;             if (tj <= ti) {
;                 const h16* As = isqk ? qn : kn;
; #pragma unroll
;                 for (int kk = 0; kk < 4; ++kk) {
;                     const h16x8 a = *(const h16x8*)(As + (16 * ti + fr) * 136 + 32 * kk + 8 * g);
;                     const h16x8 bb = *(const h16x8*)(kn + (16 * tj + fr) * 136 + 32 * kk + 8 * g);
;                     acc = MFMA16(a, bb, acc);
;                 }
;             }
; #pragma unroll
;             for (int rg = 0; rg < 4; ++rg) {
;                 const int i = 16 * ti + 4 * g + rg, j = 16 * tj + fr;
;                 const float dec = fexp(fminf(gcs[i] - gcs[j], 0.f));
;                 if (!isqk) Mm[i * 68 + j] = (j < i) ? acc[rg] * bts[i] * dec : 0.f;
;                 else gst(qkg + (bh0 + i) * 64 + j, (h16)((j <= i) ? acc[rg] * dec : 0.f));
.LBB0_406:
	v_mov_b32_e32 v0, 0
	s_andn2_b64 vcc, exec, s[28:29]
	v_mov_b32_e32 v2, 0
	v_mov_b32_e32 v3, 0
	v_mov_b32_e32 v4, 0
	v_mov_b32_e32 v5, 0
	s_cbranch_vccnz .LBB0_408
	v_readlane_b32 s0, v254, 39
	s_nop 1
	v_add3_u32 v1, s0, v25, v24
	ds_read_b128 v[228:231], v1
	ds_read_b128 v[232:235], v1 offset:64
	ds_read_b128 v[102:105], v1 offset:128
	ds_read_b128 v[106:109], v1 offset:192
	s_waitcnt lgkmcnt(3)
	v_mfma_f32_16x16x32_f16 v[2:5], v[228:231], v[236:239], 0
	s_waitcnt lgkmcnt(2)
	v_mfma_f32_16x16x32_f16 v[2:5], v[232:235], v[240:243], v[2:5]
	s_waitcnt lgkmcnt(1)
	v_mfma_f32_16x16x32_f16 v[2:5], v[102:105], v[244:247], v[2:5]
	s_waitcnt lgkmcnt(0)
	v_mfma_f32_16x16x32_f16 v[2:5], v[106:109], v[248:251], v[2:5]
.LBB0_408:
	s_nop 7
	v_fma_mixlo_f16 v1, v2, v27, 0
	v_cmp_le_u32_e32 vcc, v22, v26
	v_lshl_add_u64 v[46:47], v[32:33], 1, v[6:7]
	v_mov_b32_e32 v9, v33
	v_cndmask_b32_e32 v1, 0, v1, vcc
	global_store_short v[46:47], v1, off
	v_fma_mixlo_f16 v1, v3, v29, 0
	v_cmp_le_u32_e32 vcc, v22, v28
	v_lshl_add_u64 v[8:9], v[8:9], 1, v[6:7]
	v_mov_b32_e32 v11, v33
	v_cndmask_b32_e32 v1, 0, v1, vcc
	global_store_short v[8:9], v1, off
	v_fma_mixlo_f16 v1, v4, v31, 0
	v_cmp_le_u32_e32 vcc, v22, v30
	v_lshl_add_u64 v[2:3], v[10:11], 1, v[6:7]
	v_mov_b32_e32 v13, v33
	v_cndmask_b32_e32 v1, 0, v1, vcc
	global_store_short v[2:3], v1, off
	v_fma_mixlo_f16 v1, v5, v35, 0
	v_cmp_le_u32_e32 vcc, v22, v34
	v_lshl_add_u64 v[2:3], v[12:13], 1, v[6:7]
	s_nop 0
	v_cndmask_b32_e32 v1, 0, v1, vcc
	global_store_short v[2:3], v1, off
	s_and_b64 vcc, exec, s[4:5]
	v_mov_b32_e32 v1, 0
	v_mov_b32_e32 v2, 0
	v_mov_b32_e32 v3, 0
	s_cbranch_vccnz .LBB0_410
	v_readlane_b32 s0, v254, 39
	s_nop 1
	v_add3_u32 v4, s0, v36, v24
	ds_read_b128 v[228:231], v4
	ds_read_b128 v[232:235], v4 offset:64
	ds_read_b128 v[102:105], v4 offset:128
	ds_read_b128 v[106:109], v4 offset:192
	s_waitcnt lgkmcnt(3)
	v_mfma_f32_16x16x32_f16 v[0:3], v[228:231], v[236:239], 0
	s_waitcnt lgkmcnt(2)
	v_mfma_f32_16x16x32_f16 v[0:3], v[232:235], v[240:243], v[0:3]
	s_waitcnt lgkmcnt(1)
	v_mfma_f32_16x16x32_f16 v[0:3], v[102:105], v[244:247], v[0:3]
	s_waitcnt lgkmcnt(0)
	v_mfma_f32_16x16x32_f16 v[0:3], v[106:109], v[248:251], v[0:3]
